# MLA: 4-slot tile ring (second LDS window via biased base registers), staggered waves 4-7 meet the barrier after the 3rd QK MFMA
# baseline (speedup 1.0000x reference)
; __device__ __forceinline__ void finishSM9(f32x16& p0, f32x16& p1, float alpha, float& l_reg, v8i32& p8) {
; #pragma unroll
;   for (int r = 0; r < 16; ++r) { p0[r] = __builtin_amdgcn_exp2f(p0[r]); p1[r] = __builtin_amdgcn_exp2f(p1[r]); }
;   float ps = 0;
; #pragma unroll
;   for (int r = 0; r < 16; ++r) ps += p0[r];
; #pragma unroll
;   for (int r = 0; r < 16; ++r) ps += p1[r];
;   { auto rr = __builtin_amdgcn_permlane32_swap(__float_as_uint(ps), __float_as_uint(ps), false, false);
;     ps = __uint_as_float(rr[0]) + __uint_as_float(rr[1]); }
;   l_reg = l_reg * alpha + ps;
; #pragma unroll
;   for (int g = 0; g < 4; ++g) {
;     int w = __builtin_amdgcn_cvt_pk_fp8_f32(p0[4 * g], p0[4 * g + 1], 0, false); p8[g] = __builtin_amdgcn_cvt_pk_fp8_f32(p0[4 * g + 2], p0[4 * g + 3], w, true);
;     int u = __builtin_amdgcn_cvt_pk_fp8_f32(p1[4 * g], p1[4 * g + 1], 0, false); p8[4 + g] = __builtin_amdgcn_cvt_pk_fp8_f32(p1[4 * g + 2], p1[4 * g + 3], u, true); }
; }
; __device__ __forceinline__ void pv8(f32x16* o, const char* Vt, const v8i32 p8, int r32, int hi) {
; __device__ __forceinline__ void attn_unit7(const unsigned char* __restrict__ Q8, int ldq, const unsigned char* __restrict__ Kn8, int ldk, const unsigned char* __restrict__ Kr8, ...
;     ...
;   float m_reg = 0.f, l_reg = 0; f32x16 o[4] = {}; v8i32 qf[3];
;   { const unsigned char* Qw = Q8 + (unsigned)((wid * 32 + r32) * ldq + hi * 32);
; #pragma unroll
;     for (int s = 0; s < 3; ++s) qf[s] = cat8(*reinterpret_cast<const v4i32*>(Qw + s * 64), *reinterpret_cast<const v4i32*>(Qw + s * 64 + 16)); }
;   const int vtr = tid >> 2, vtc = tid & 3, vtst = vtr * 64 + ((vtc ^ ((vtr >> 2) & 3)) << 4);
;   const int knr = tid >> 3, knc = tid & 7, knst = KN8SW(knr, knc);
;   const int krr = (tid >> 2) & 63, krc = tid & 3, krst = KR8SW(krr, krc);
;   const bool krw = tid < 256;
;   unsigned vtoff = (unsigned)(tid * 16), knoff = (unsigned)(knr * ldk + knc * 16), kroff = (unsigned)(krr * 64 + krc * 16);
;   v4i32 vt, kn, kr;
;     ...
;   f32x16 pA0, pA1, pB0, pB1; float alA, alB; v8i32 p8;
;   SLOAD(); SWRITE(0); __syncthreads();
;   SLOAD();
;   qkt9(pA0, pA1, Kn_lds, Kr_lds, qf, 7.0f - m_reg, r32, hi); partialSM9(pA0, pA1, m_reg, alA, thr_raw);
;   SWRITE(1); __syncthreads();
;   for (int j = 1; j + 1 < NT; j += 2) {
;     SLOAD();
;     qkt9(pB0, pB1, Kn_lds + 8192, Kr_lds + 4096, qf, 7.0f - m_reg, r32, hi);
.LBB0_1320:
	s_or_b64 exec, exec, s[20:21]
	v_and_b32_e32 v0, 0x3fffffc0, v12
	s_mov_b32 s20, 0x60000
	v_lshl_add_u32 v187, v0, 2, 0
	v_add3_u32 v178, v13, v14, s20
	v_add_u32_e32 v0, v15, v16
	v_mov_b32_e32 v14, v1
	v_mov_b32_e32 v15, v1
	v_and_b32_e32 v184, 63, v12
	v_lshl_add_u64 v[180:181], s[12:13], 0, v[0:1]
	v_mov_b32_e32 v0, v1
	v_mov_b32_e32 v2, v1
	v_mov_b32_e32 v3, v1
	v_mov_b32_e32 v4, v1
	v_mov_b32_e32 v5, v1
	v_mov_b32_e32 v6, v1
	v_mov_b32_e32 v7, v1
	v_mov_b32_e32 v8, v1
	v_mov_b32_e32 v9, v1
	v_mov_b32_e32 v10, v1
	v_mov_b32_e32 v11, v1
	v_mov_b32_e32 v12, v1
	v_mov_b32_e32 v13, v1
	v_mov_b64_e32 v[64:65], v[14:15]
	v_mov_b64_e32 v[48:49], v[14:15]
	v_mov_b64_e32 v[32:33], v[14:15]
	v_mov_b64_e32 v[62:63], v[12:13]
	v_mov_b64_e32 v[60:61], v[10:11]
	v_mov_b64_e32 v[58:59], v[8:9]
	v_mov_b64_e32 v[56:57], v[6:7]
	v_mov_b64_e32 v[54:55], v[4:5]
	v_mov_b64_e32 v[52:53], v[2:3]
	v_mov_b64_e32 v[50:51], v[0:1]
	v_mov_b64_e32 v[46:47], v[12:13]
	v_mov_b64_e32 v[44:45], v[10:11]
	v_mov_b64_e32 v[42:43], v[8:9]
	v_mov_b64_e32 v[40:41], v[6:7]
	v_mov_b64_e32 v[38:39], v[4:5]
	v_mov_b64_e32 v[36:37], v[2:3]
	v_mov_b64_e32 v[34:35], v[0:1]
	v_mov_b64_e32 v[30:31], v[12:13]
	v_mov_b64_e32 v[28:29], v[10:11]
	v_mov_b64_e32 v[26:27], v[8:9]
	v_mov_b64_e32 v[24:25], v[6:7]
	v_mov_b64_e32 v[22:23], v[4:5]
	v_mov_b64_e32 v[20:21], v[2:3]
	v_mov_b64_e32 v[18:19], v[0:1]
	v_mov_b64_e32 v[16:17], v[14:15]
	s_lshl_b32 s29, s29, 8
	v_cmp_gt_u32_e64 s[40:41], 32, v184
	v_lshl_add_u32 v208, v183, 2, v187
	v_lshlrev_b32_e32 v207, 4, v175
	v_add_u32_e32 v176, 0x6000, v174
	v_mov_b32_e32 v209, 0
	s_mov_b32 s30, -1
	v_mov_b64_e32 v[14:15], v[12:13]
	v_mov_b64_e32 v[12:13], v[10:11]
	v_mov_b64_e32 v[10:11], v[8:9]
	v_mov_b64_e32 v[8:9], v[6:7]
	v_mov_b64_e32 v[6:7], v[4:5]
	v_mov_b64_e32 v[4:5], v[2:3]
	v_mov_b64_e32 v[2:3], v[0:1]
	v_add_u32_e32 v176, 0xffffe000, v176
	v_add_u32_e32 v178, 0xfffe0000, v178
	v_sub_f32_e32 v230, 0x40e00000, v217
	v_mov_b32_e32 v231, v230
	v_mov_b32_e32 v232, v230
	v_mov_b32_e32 v233, v230
	v_mov_b32_e32 v234, v230
	v_mov_b32_e32 v235, v230
	v_mov_b32_e32 v236, v230
	v_mov_b32_e32 v237, v230
	v_mov_b32_e32 v238, v230
	v_mov_b32_e32 v239, v230
	v_mov_b32_e32 v240, v230
	v_mov_b32_e32 v241, v230
	v_mov_b32_e32 v242, v230
	v_mov_b32_e32 v243, v230
	v_mov_b32_e32 v244, v230
	v_mov_b32_e32 v245, v230
	s_mov_b32 s30, 0
	v_add_u32_e32 v170, 0xa800, v185
	v_add_u32_e32 v171, 0xa800, v186
	v_add_u32_e32 v172, 0xa800, v210
	v_add_u32_e32 v173, 0xa800, v211
	v_add_u32_e32 v220, 0xa800, v212
	v_add_u32_e32 v168, 0xa800, v213
	v_add_u32_e32 v169, 0xa800, v214
	v_add_u32_e32 v166, 0xa800, v215
	v_add_u32_e32 v167, 0xa800, v216
	s_waitcnt lgkmcnt(0)
	s_barrier
	s_cmp_eq_u64 s[42:43], 0
	s_cbranch_scc1 .Lmla_stag_entry
.LBB0_1321:
	global_load_dwordx4 v[158:161], v176, s[18:19]
	global_load_dwordx4 v[162:165], v178, s[16:17]
	global_load_dwordx4 v[154:157], v[180:181], off
	ds_read_b128 v[114:117], v215 offset:24576
	ds_read_b128 v[118:121], v216 offset:24576
	ds_read_b128 v[222:225], v215 offset:28672
	ds_read_b128 v[226:229], v216 offset:28672
	v_add_u32_e32 v176, 0x2000, v176
	v_add_u32_e32 v178, 0x20000, v178
	s_mov_b64 s[20:21], 0x1000
	v_lshl_add_u64 v[180:181], v[180:181], 0, s[20:21]
	v_exp_f32_e32 v0, v82
	v_exp_f32_e32 v177, v83
	v_exp_f32_e32 v179, v84
	v_exp_f32_e32 v254, v85
	v_add_f32_e32 v219, v0, v177
	v_cvt_pk_fp8_f32 v246, v0, v177
	v_add_f32_e32 v219, v179, v219
	v_add_f32_e32 v219, v254, v219
	v_cvt_pk_fp8_f32 v246, v179, v254 op_sel:[0,0,1]
	s_waitcnt lgkmcnt(2)
	v_mfma_scale_f32_32x32x64_f8f6f4 v[114:129], v[114:121], v[146:153], v[230:245], v194, v193 op_sel_hi:[0,0,0]
	v_exp_f32_e32 v0, v86
	v_exp_f32_e32 v177, v87
	v_exp_f32_e32 v179, v88
	v_exp_f32_e32 v254, v89
	v_add_f32_e32 v219, v0, v219
	v_add_f32_e32 v219, v177, v219
	v_cvt_pk_fp8_f32 v247, v0, v177
	v_add_f32_e32 v219, v179, v219
	v_add_f32_e32 v219, v254, v219
	v_cvt_pk_fp8_f32 v247, v179, v254 op_sel:[0,0,1]
	ds_read_b128 v[82:85], v213 offset:24576
	ds_read_b128 v[86:89], v214 offset:24576
	s_waitcnt lgkmcnt(2)
	v_mfma_scale_f32_32x32x64_f8f6f4 v[98:113], v[222:229], v[146:153], v[230:245], v194, v193 op_sel_hi:[0,0,0]
	ds_read_b128 v[222:225], v213 offset:28672
	ds_read_b128 v[226:229], v214 offset:28672
	v_exp_f32_e32 v0, v90
	v_exp_f32_e32 v177, v91
	v_exp_f32_e32 v179, v92
	v_exp_f32_e32 v254, v93
	v_add_f32_e32 v219, v0, v219
	v_add_f32_e32 v219, v177, v219
	v_cvt_pk_fp8_f32 v248, v0, v177
	v_add_f32_e32 v219, v179, v219
	v_add_f32_e32 v219, v254, v219
	v_cvt_pk_fp8_f32 v248, v179, v254 op_sel:[0,0,1]
	v_exp_f32_e32 v0, v94
	v_exp_f32_e32 v177, v95
	v_exp_f32_e32 v179, v96
	v_exp_f32_e32 v254, v97
	v_add_f32_e32 v219, v0, v219
	v_add_f32_e32 v219, v177, v219
	v_cvt_pk_fp8_f32 v249, v0, v177
	v_add_f32_e32 v219, v179, v219
	v_add_f32_e32 v219, v254, v219
	v_cvt_pk_fp8_f32 v249, v179, v254 op_sel:[0,0,1]
	ds_read_b128 v[90:93], v185 offset:36864
	ds_read_b128 v[94:97], v186 offset:36864
	s_waitcnt lgkmcnt(4)
	v_mfma_scale_f32_32x32x64_f8f6f4 v[114:129], v[82:89], v[138:145], v[114:129], v194, v193 op_sel_hi:[0,0,0]
	v_exp_f32_e32 v0, v66
	v_exp_f32_e32 v177, v67
	v_exp_f32_e32 v179, v68
	v_exp_f32_e32 v254, v69
	v_add_f32_e32 v219, v0, v219
	v_add_f32_e32 v219, v177, v219
	v_cvt_pk_fp8_f32 v250, v0, v177
	v_add_f32_e32 v219, v179, v219
	v_add_f32_e32 v219, v254, v219
	v_cvt_pk_fp8_f32 v250, v179, v254 op_sel:[0,0,1]
	s_waitcnt lgkmcnt(2)
; __device__ __forceinline__ void finishSM9(f32x16& p0, f32x16& p1, float alpha, float& l_reg, v8i32& p8) {
; #pragma unroll
;   for (int r = 0; r < 16; ++r) { p0[r] = __builtin_amdgcn_exp2f(p0[r]); p1[r] = __builtin_amdgcn_exp2f(p1[r]); }
;   float ps = 0;
; #pragma unroll
;   for (int r = 0; r < 16; ++r) ps += p0[r];
; #pragma unroll
;   for (int r = 0; r < 16; ++r) ps += p1[r];
;   { auto rr = __builtin_amdgcn_permlane32_swap(__float_as_uint(ps), __float_as_uint(ps), false, false);
;     ps = __uint_as_float(rr[0]) + __uint_as_float(rr[1]); }
;   l_reg = l_reg * alpha + ps;
; #pragma unroll
;   for (int g = 0; g < 4; ++g) {
;     int w = __builtin_amdgcn_cvt_pk_fp8_f32(p0[4 * g], p0[4 * g + 1], 0, false); p8[g] = __builtin_amdgcn_cvt_pk_fp8_f32(p0[4 * g + 2], p0[4 * g + 3], w, true);
;     int u = __builtin_amdgcn_cvt_pk_fp8_f32(p1[4 * g], p1[4 * g + 1], 0, false); p8[4 + g] = __builtin_amdgcn_cvt_pk_fp8_f32(p1[4 * g + 2], p1[4 * g + 3], u, true); }
; }
; __device__ __forceinline__ void pv8(f32x16* o, const char* Vt, const v8i32 p8, int r32, int hi) {
;   const int sw = (r32 >> 2) & 3, a0 = r32 * 64 + (((hi * 2) ^ sw) << 4), a1 = r32 * 64 + (((hi * 2 + 1) ^ sw) << 4);
; #pragma unroll
;   for (int d0 = 0; d0 < 4; ++d0) {
;     const v8i32 vf = cat8(*reinterpret_cast<const v4i32*>(Vt + d0 * 2048 + a0), *reinterpret_cast<const v4i32*>(Vt + d0 * 2048 + a1));
;     o[d0] = __builtin_amdgcn_mfma_scale_f32_32x32x64_f8f6f4(p8, vf, o[d0], 0, 0, 0, 127, 0, 127); }
; }
; __device__ __forceinline__ void attn_unit7(const unsigned char* __restrict__ Q8, int ldq, const unsigned char* __restrict__ Kn8, int ldk, const unsigned char* __restrict__ Kr8, ...
;     ...
;   for (int j = 1; j + 1 < NT; j += 2) {
;     SLOAD();
;     qkt9(pB0, pB1, Kn_lds + 8192, Kr_lds + 4096, qf, 7.0f - m_reg, r32, hi);
;     finishSM9(pA0, pA1, alA, l_reg, p8);
;     pv8(o, Vt_lds, p8, r32, hi); partialSM9(pB0, pB1, m_reg, alB, thr_raw);
;     __syncthreads(); SWRITE(0);
;     RESC(alB); __syncthreads();
;     if (j + 2 < NT) SLOAD();
;     qkt9(pA0, pA1, Kn_lds, Kr_lds, qf, 7.0f - m_reg, r32, hi);
;     finishSM9(pB0, pB1, alB, l_reg, p8);
;     pv8(o, Vt_lds + 8192, p8, r32, hi); partialSM9(pA0, pA1, m_reg, alA, thr_raw);
;     __syncthreads(); if (j + 2 < NT) SWRITE(1);
;     RESC(alA); __syncthreads();
	v_mfma_scale_f32_32x32x64_f8f6f4 v[98:113], v[222:229], v[138:145], v[98:113], v194, v193 op_sel_hi:[0,0,0]
	ds_read_b128 v[222:225], v185 offset:38912
	ds_read_b128 v[226:229], v186 offset:38912
	v_exp_f32_e32 v0, v70
	v_exp_f32_e32 v177, v71
	v_exp_f32_e32 v179, v72
	v_exp_f32_e32 v254, v73
	v_add_f32_e32 v219, v0, v219
	v_add_f32_e32 v219, v177, v219
	v_cvt_pk_fp8_f32 v251, v0, v177
	v_add_f32_e32 v219, v179, v219
	v_add_f32_e32 v219, v254, v219
	v_cvt_pk_fp8_f32 v251, v179, v254 op_sel:[0,0,1]
	v_exp_f32_e32 v0, v74
	v_exp_f32_e32 v177, v75
	v_exp_f32_e32 v179, v76
	v_exp_f32_e32 v254, v77
	v_add_f32_e32 v219, v0, v219
	v_add_f32_e32 v219, v177, v219
	v_cvt_pk_fp8_f32 v252, v0, v177
	v_add_f32_e32 v219, v179, v219
	v_add_f32_e32 v219, v254, v219
	v_cvt_pk_fp8_f32 v252, v179, v254 op_sel:[0,0,1]
	s_waitcnt lgkmcnt(2)
	v_mfma_scale_f32_32x32x64_f8f6f4 v[114:129], v[90:97], v[130:137], v[114:129], v194, v193 op_sel_hi:[0,0,0]
	v_exp_f32_e32 v0, v78
	v_exp_f32_e32 v177, v79
	v_exp_f32_e32 v179, v80
	v_exp_f32_e32 v254, v81
	v_add_f32_e32 v219, v0, v219
	v_add_f32_e32 v219, v177, v219
	v_cvt_pk_fp8_f32 v253, v0, v177
	v_add_f32_e32 v219, v179, v219
	v_add_f32_e32 v219, v254, v219
	v_cvt_pk_fp8_f32 v253, v179, v254 op_sel:[0,0,1]
	ds_read_b128 v[90:93], v185 offset:0
	ds_read_b128 v[94:97], v186 offset:0
	ds_read_b128 v[82:85], v185 offset:2048
	ds_read_b128 v[86:89], v186 offset:2048
	ds_read_b128 v[74:77], v185 offset:4096
	ds_read_b128 v[78:81], v186 offset:4096
	ds_read_b128 v[66:69], v185 offset:6144
	ds_read_b128 v[70:73], v186 offset:6144
	s_waitcnt lgkmcnt(8)
	v_mfma_scale_f32_32x32x64_f8f6f4 v[98:113], v[222:229], v[130:137], v[98:113], v194, v193 op_sel_hi:[0,0,0]
	v_mov_b32_e32 v0, v219
	s_nop 1
	v_permlane32_swap_b32_e32 v219, v0
	v_add_f32_e32 v219, v219, v0
	v_fma_f32 v209, v209, v218, v219
	v_max_f32_e32 v177, v114, v115
	v_max3_f32 v177, v177, v116, v117
	v_max3_f32 v177, v177, v118, v119
	v_max3_f32 v177, v177, v120, v121
	v_max3_f32 v177, v177, v122, v123
	v_max3_f32 v177, v177, v124, v125
	v_max3_f32 v177, v177, v126, v127
	v_max3_f32 v177, v177, v128, v129
	s_waitcnt lgkmcnt(6)
	v_mfma_scale_f32_32x32x64_f8f6f4 v[50:65], v[246:253], v[90:97], v[50:65], v194, v194 op_sel_hi:[0,0,0]
	s_waitcnt lgkmcnt(4)
	v_mfma_scale_f32_32x32x64_f8f6f4 v[34:49], v[246:253], v[82:89], v[34:49], v194, v194 op_sel_hi:[0,0,0]
	s_waitcnt lgkmcnt(2)
	v_mfma_scale_f32_32x32x64_f8f6f4 v[18:33], v[246:253], v[74:81], v[18:33], v194, v194 op_sel_hi:[0,0,0]
	s_waitcnt lgkmcnt(0)
	v_mfma_scale_f32_32x32x64_f8f6f4 v[2:17], v[246:253], v[66:73], v[2:17], v194, v194 op_sel_hi:[0,0,0]
	s_waitcnt vmcnt(0)
	ds_write_b128 v172, v[158:161]
	ds_write_b128 v173, v[162:165] offset:16384
	ds_write_b128 v220, v[154:157] offset:32768
	v_max_f32_e32 v0, v98, v99
	v_max3_f32 v0, v0, v100, v101
	v_max3_f32 v0, v0, v102, v103
	v_max3_f32 v0, v0, v104, v105
	v_max3_f32 v0, v0, v106, v107
	v_max3_f32 v0, v0, v108, v109
	v_max3_f32 v0, v0, v110, v111
	v_max3_f32 v0, v0, v112, v113
	v_max_f32_e32 v177, v177, v0
	v_mov_b32_e32 v0, v177
	v_mov_b32_e32 v221, 1.0
	s_nop 0
	v_permlane32_swap_b32_e32 v177, v0
	v_max_f32_e32 v177, v177, v0
	v_cmp_ge_f32_e32 vcc, s90, v177
	s_cmp_eq_u64 vcc, exec
	s_cbranch_scc0 .Lmla_h0_newmax
.Lmla_h0_cont:
	s_waitcnt lgkmcnt(0)
	s_barrier
	global_load_dwordx4 v[158:161], v176, s[18:19]
	global_load_dwordx4 v[162:165], v178, s[16:17]
	global_load_dwordx4 v[154:157], v[180:181], off
	ds_read_b128 v[82:85], v166 offset:16384
	ds_read_b128 v[86:89], v167 offset:16384
	ds_read_b128 v[222:225], v166 offset:20480
	ds_read_b128 v[226:229], v167 offset:20480
	v_add_u32_e32 v176, 0x2000, v176
	v_add_u32_e32 v178, 0x20000, v178
	s_mov_b64 s[20:21], 0x1000
	v_lshl_add_u64 v[180:181], v[180:181], 0, s[20:21]
	v_exp_f32_e32 v0, v114
	v_exp_f32_e32 v177, v115
	v_exp_f32_e32 v179, v116
	v_exp_f32_e32 v254, v117
	v_add_f32_e32 v219, v0, v177
	v_cvt_pk_fp8_f32 v246, v0, v177
	v_add_f32_e32 v219, v179, v219
	v_add_f32_e32 v219, v254, v219
	v_cvt_pk_fp8_f32 v246, v179, v254 op_sel:[0,0,1]
	s_waitcnt lgkmcnt(2)
	v_mfma_scale_f32_32x32x64_f8f6f4 v[82:97], v[82:89], v[146:153], v[230:245], v194, v193 op_sel_hi:[0,0,0]
	v_exp_f32_e32 v0, v118
	v_exp_f32_e32 v177, v119
	v_exp_f32_e32 v179, v120
	v_exp_f32_e32 v254, v121
	v_add_f32_e32 v219, v0, v219
	v_add_f32_e32 v219, v177, v219
	v_cvt_pk_fp8_f32 v247, v0, v177
	v_add_f32_e32 v219, v179, v219
	v_add_f32_e32 v219, v254, v219
	v_cvt_pk_fp8_f32 v247, v179, v254 op_sel:[0,0,1]
	ds_read_b128 v[114:117], v168 offset:16384
	ds_read_b128 v[118:121], v169 offset:16384
	s_waitcnt lgkmcnt(2)
	v_mfma_scale_f32_32x32x64_f8f6f4 v[66:81], v[222:229], v[146:153], v[230:245], v194, v193 op_sel_hi:[0,0,0]
	ds_read_b128 v[222:225], v168 offset:20480
	ds_read_b128 v[226:229], v169 offset:20480
	v_exp_f32_e32 v0, v122
	v_exp_f32_e32 v177, v123
	v_exp_f32_e32 v179, v124
	v_exp_f32_e32 v254, v125
	v_add_f32_e32 v219, v0, v219
	v_add_f32_e32 v219, v177, v219
	v_cvt_pk_fp8_f32 v248, v0, v177
	v_add_f32_e32 v219, v179, v219
	v_add_f32_e32 v219, v254, v219
	v_cvt_pk_fp8_f32 v248, v179, v254 op_sel:[0,0,1]
	v_exp_f32_e32 v0, v126
	v_exp_f32_e32 v177, v127
	v_exp_f32_e32 v179, v128
	v_exp_f32_e32 v254, v129
	v_add_f32_e32 v219, v0, v219
	v_add_f32_e32 v219, v177, v219
	v_cvt_pk_fp8_f32 v249, v0, v177
	v_add_f32_e32 v219, v179, v219
	v_add_f32_e32 v219, v254, v219
	v_cvt_pk_fp8_f32 v249, v179, v254 op_sel:[0,0,1]
	ds_read_b128 v[122:125], v170 offset:32768
	ds_read_b128 v[126:129], v171 offset:32768
	s_waitcnt lgkmcnt(4)
; __device__ __forceinline__ void finishSM9(f32x16& p0, f32x16& p1, float alpha, float& l_reg, v8i32& p8) {
; #pragma unroll
;   for (int r = 0; r < 16; ++r) { p0[r] = __builtin_amdgcn_exp2f(p0[r]); p1[r] = __builtin_amdgcn_exp2f(p1[r]); }
;   float ps = 0;
; #pragma unroll
;   for (int r = 0; r < 16; ++r) ps += p0[r];
; #pragma unroll
;   for (int r = 0; r < 16; ++r) ps += p1[r];
;   { auto rr = __builtin_amdgcn_permlane32_swap(__float_as_uint(ps), __float_as_uint(ps), false, false);
;     ps = __uint_as_float(rr[0]) + __uint_as_float(rr[1]); }
;   l_reg = l_reg * alpha + ps;
; #pragma unroll
;   for (int g = 0; g < 4; ++g) {
;     int w = __builtin_amdgcn_cvt_pk_fp8_f32(p0[4 * g], p0[4 * g + 1], 0, false); p8[g] = __builtin_amdgcn_cvt_pk_fp8_f32(p0[4 * g + 2], p0[4 * g + 3], w, true);
;     int u = __builtin_amdgcn_cvt_pk_fp8_f32(p1[4 * g], p1[4 * g + 1], 0, false); p8[4 + g] = __builtin_amdgcn_cvt_pk_fp8_f32(p1[4 * g + 2], p1[4 * g + 3], u, true); }
; }
; __device__ __forceinline__ void pv8(f32x16* o, const char* Vt, const v8i32 p8, int r32, int hi) {
;   const int sw = (r32 >> 2) & 3, a0 = r32 * 64 + (((hi * 2) ^ sw) << 4), a1 = r32 * 64 + (((hi * 2 + 1) ^ sw) << 4);
; #pragma unroll
;   for (int d0 = 0; d0 < 4; ++d0) {
;     const v8i32 vf = cat8(*reinterpret_cast<const v4i32*>(Vt + d0 * 2048 + a0), *reinterpret_cast<const v4i32*>(Vt + d0 * 2048 + a1));
;     o[d0] = __builtin_amdgcn_mfma_scale_f32_32x32x64_f8f6f4(p8, vf, o[d0], 0, 0, 0, 127, 0, 127); }
; }
; __device__ __forceinline__ void attn_unit7(const unsigned char* __restrict__ Q8, int ldq, const unsigned char* __restrict__ Kn8, int ldk, const unsigned char* __restrict__ Kr8, ...
;     ...
;   for (int j = 1; j + 1 < NT; j += 2) {
;     SLOAD();
;     qkt9(pB0, pB1, Kn_lds + 8192, Kr_lds + 4096, qf, 7.0f - m_reg, r32, hi);
;     finishSM9(pA0, pA1, alA, l_reg, p8);
;     pv8(o, Vt_lds, p8, r32, hi); partialSM9(pB0, pB1, m_reg, alB, thr_raw);
;     __syncthreads(); SWRITE(0);
;     RESC(alB); __syncthreads();
;     if (j + 2 < NT) SLOAD();
;     qkt9(pA0, pA1, Kn_lds, Kr_lds, qf, 7.0f - m_reg, r32, hi);
;     finishSM9(pB0, pB1, alB, l_reg, p8);
;     pv8(o, Vt_lds + 8192, p8, r32, hi); partialSM9(pA0, pA1, m_reg, alA, thr_raw);
;     __syncthreads(); if (j + 2 < NT) SWRITE(1);
;     RESC(alA); __syncthreads();
	v_mfma_scale_f32_32x32x64_f8f6f4 v[82:97], v[114:121], v[138:145], v[82:97], v194, v193 op_sel_hi:[0,0,0]
	v_exp_f32_e32 v0, v98
	v_exp_f32_e32 v177, v99
	v_exp_f32_e32 v179, v100
	v_exp_f32_e32 v254, v101
	v_add_f32_e32 v219, v0, v219
	v_add_f32_e32 v219, v177, v219
	v_cvt_pk_fp8_f32 v250, v0, v177
	v_add_f32_e32 v219, v179, v219
	v_add_f32_e32 v219, v254, v219
	v_cvt_pk_fp8_f32 v250, v179, v254 op_sel:[0,0,1]
	s_waitcnt lgkmcnt(2)
	v_mfma_scale_f32_32x32x64_f8f6f4 v[66:81], v[222:229], v[138:145], v[66:81], v194, v193 op_sel_hi:[0,0,0]
	ds_read_b128 v[222:225], v170 offset:34816
	ds_read_b128 v[226:229], v171 offset:34816
	v_exp_f32_e32 v0, v102
	v_exp_f32_e32 v177, v103
	v_exp_f32_e32 v179, v104
	v_exp_f32_e32 v254, v105
	v_add_f32_e32 v219, v0, v219
	v_add_f32_e32 v219, v177, v219
	v_cvt_pk_fp8_f32 v251, v0, v177
	v_add_f32_e32 v219, v179, v219
	v_add_f32_e32 v219, v254, v219
	v_cvt_pk_fp8_f32 v251, v179, v254 op_sel:[0,0,1]
	v_exp_f32_e32 v0, v106
	v_exp_f32_e32 v177, v107
	v_exp_f32_e32 v179, v108
	v_exp_f32_e32 v254, v109
	v_add_f32_e32 v219, v0, v219
	v_add_f32_e32 v219, v177, v219
	v_cvt_pk_fp8_f32 v252, v0, v177
	v_add_f32_e32 v219, v179, v219
	v_add_f32_e32 v219, v254, v219
	v_cvt_pk_fp8_f32 v252, v179, v254 op_sel:[0,0,1]
	s_waitcnt lgkmcnt(2)
	v_mfma_scale_f32_32x32x64_f8f6f4 v[82:97], v[122:129], v[130:137], v[82:97], v194, v193 op_sel_hi:[0,0,0]
	v_exp_f32_e32 v0, v110
	v_exp_f32_e32 v177, v111
	v_exp_f32_e32 v179, v112
	v_exp_f32_e32 v254, v113
	v_add_f32_e32 v219, v0, v219
	v_add_f32_e32 v219, v177, v219
	v_cvt_pk_fp8_f32 v253, v0, v177
	v_add_f32_e32 v219, v179, v219
	v_add_f32_e32 v219, v254, v219
	v_cvt_pk_fp8_f32 v253, v179, v254 op_sel:[0,0,1]
	ds_read_b128 v[122:125], v185 offset:8192
	ds_read_b128 v[126:129], v186 offset:8192
	ds_read_b128 v[114:117], v185 offset:10240
	ds_read_b128 v[118:121], v186 offset:10240
	ds_read_b128 v[106:109], v185 offset:12288
	ds_read_b128 v[110:113], v186 offset:12288
	ds_read_b128 v[98:101], v185 offset:14336
	ds_read_b128 v[102:105], v186 offset:14336
	s_waitcnt lgkmcnt(8)
	v_mfma_scale_f32_32x32x64_f8f6f4 v[66:81], v[222:229], v[130:137], v[66:81], v194, v193 op_sel_hi:[0,0,0]
	v_mov_b32_e32 v0, v219
	s_nop 1
	v_permlane32_swap_b32_e32 v219, v0
	v_add_f32_e32 v219, v219, v0
	v_fma_f32 v209, v209, v221, v219
	v_max_f32_e32 v177, v82, v83
	v_max3_f32 v177, v177, v84, v85
	v_max3_f32 v177, v177, v86, v87
	v_max3_f32 v177, v177, v88, v89
	v_max3_f32 v177, v177, v90, v91
	v_max3_f32 v177, v177, v92, v93
	v_max3_f32 v177, v177, v94, v95
	v_max3_f32 v177, v177, v96, v97
	s_waitcnt lgkmcnt(6)
	v_mfma_scale_f32_32x32x64_f8f6f4 v[50:65], v[246:253], v[122:129], v[50:65], v194, v194 op_sel_hi:[0,0,0]
	s_waitcnt lgkmcnt(4)
	v_mfma_scale_f32_32x32x64_f8f6f4 v[34:49], v[246:253], v[114:121], v[34:49], v194, v194 op_sel_hi:[0,0,0]
	s_waitcnt lgkmcnt(2)
	v_mfma_scale_f32_32x32x64_f8f6f4 v[18:33], v[246:253], v[106:113], v[18:33], v194, v194 op_sel_hi:[0,0,0]
	s_waitcnt lgkmcnt(0)
	v_mfma_scale_f32_32x32x64_f8f6f4 v[2:17], v[246:253], v[98:105], v[2:17], v194, v194 op_sel_hi:[0,0,0]
	s_waitcnt vmcnt(0)
	ds_write_b128 v172, v[158:161] offset:8192
	ds_write_b128 v173, v[162:165] offset:24576
	ds_write_b128 v220, v[154:157] offset:36864
	v_max_f32_e32 v0, v66, v67
	v_max3_f32 v0, v0, v68, v69
	v_max3_f32 v0, v0, v70, v71
	v_max3_f32 v0, v0, v72, v73
	v_max3_f32 v0, v0, v74, v75
	v_max3_f32 v0, v0, v76, v77
	v_max3_f32 v0, v0, v78, v79
	v_max3_f32 v0, v0, v80, v81
	v_max_f32_e32 v177, v177, v0
	v_mov_b32_e32 v0, v177
	v_mov_b32_e32 v218, 1.0
	s_nop 0
	v_permlane32_swap_b32_e32 v177, v0
	v_max_f32_e32 v177, v177, v0
	v_cmp_ge_f32_e32 vcc, s90, v177
	s_cmp_eq_u64 vcc, exec
	s_cbranch_scc0 .Lmla_h1_newmax
.Lmla_h1_cont:
	s_waitcnt lgkmcnt(0)
	s_barrier
	global_load_dwordx4 v[158:161], v176, s[18:19]
	global_load_dwordx4 v[162:165], v178, s[16:17]
	global_load_dwordx4 v[154:157], v[180:181], off
	ds_read_b128 v[114:117], v166 offset:24576
	ds_read_b128 v[118:121], v167 offset:24576
	ds_read_b128 v[222:225], v166 offset:28672
	ds_read_b128 v[226:229], v167 offset:28672
	v_add_u32_e32 v176, 0x2000, v176
	v_add_u32_e32 v178, 0x20000, v178
	s_mov_b64 s[20:21], 0x1000
	v_lshl_add_u64 v[180:181], v[180:181], 0, s[20:21]
	v_exp_f32_e32 v0, v82
	v_exp_f32_e32 v177, v83
	v_exp_f32_e32 v179, v84
	v_exp_f32_e32 v254, v85
	v_add_f32_e32 v219, v0, v177
	v_cvt_pk_fp8_f32 v246, v0, v177
	v_add_f32_e32 v219, v179, v219
	v_add_f32_e32 v219, v254, v219
	v_cvt_pk_fp8_f32 v246, v179, v254 op_sel:[0,0,1]
	s_waitcnt lgkmcnt(2)
	v_mfma_scale_f32_32x32x64_f8f6f4 v[114:129], v[114:121], v[146:153], v[230:245], v194, v193 op_sel_hi:[0,0,0]
	v_exp_f32_e32 v0, v86
	v_exp_f32_e32 v177, v87
	v_exp_f32_e32 v179, v88
	v_exp_f32_e32 v254, v89
	v_add_f32_e32 v219, v0, v219
	v_add_f32_e32 v219, v177, v219
	v_cvt_pk_fp8_f32 v247, v0, v177
	v_add_f32_e32 v219, v179, v219
	v_add_f32_e32 v219, v254, v219
	v_cvt_pk_fp8_f32 v247, v179, v254 op_sel:[0,0,1]
	ds_read_b128 v[82:85], v168 offset:24576
	ds_read_b128 v[86:89], v169 offset:24576
	s_waitcnt lgkmcnt(2)
	v_mfma_scale_f32_32x32x64_f8f6f4 v[98:113], v[222:229], v[146:153], v[230:245], v194, v193 op_sel_hi:[0,0,0]
	ds_read_b128 v[222:225], v168 offset:28672
	ds_read_b128 v[226:229], v169 offset:28672
	v_exp_f32_e32 v0, v90
	v_exp_f32_e32 v177, v91
	v_exp_f32_e32 v179, v92
	v_exp_f32_e32 v254, v93
	v_add_f32_e32 v219, v0, v219
	v_add_f32_e32 v219, v177, v219
	v_cvt_pk_fp8_f32 v248, v0, v177
	v_add_f32_e32 v219, v179, v219
	v_add_f32_e32 v219, v254, v219
	v_cvt_pk_fp8_f32 v248, v179, v254 op_sel:[0,0,1]
	v_exp_f32_e32 v0, v94
	v_exp_f32_e32 v177, v95
	v_exp_f32_e32 v179, v96
	v_exp_f32_e32 v254, v97
	v_add_f32_e32 v219, v0, v219
	v_add_f32_e32 v219, v177, v219
	v_cvt_pk_fp8_f32 v249, v0, v177
	v_add_f32_e32 v219, v179, v219
	v_add_f32_e32 v219, v254, v219
	v_cvt_pk_fp8_f32 v249, v179, v254 op_sel:[0,0,1]
	ds_read_b128 v[90:93], v170 offset:36864
	ds_read_b128 v[94:97], v171 offset:36864
	s_waitcnt lgkmcnt(4)
; __device__ __forceinline__ void finishSM9(f32x16& p0, f32x16& p1, float alpha, float& l_reg, v8i32& p8) {
; #pragma unroll
;   for (int r = 0; r < 16; ++r) { p0[r] = __builtin_amdgcn_exp2f(p0[r]); p1[r] = __builtin_amdgcn_exp2f(p1[r]); }
;   float ps = 0;
; #pragma unroll
;   for (int r = 0; r < 16; ++r) ps += p0[r];
; #pragma unroll
;   for (int r = 0; r < 16; ++r) ps += p1[r];
;   { auto rr = __builtin_amdgcn_permlane32_swap(__float_as_uint(ps), __float_as_uint(ps), false, false);
;     ps = __uint_as_float(rr[0]) + __uint_as_float(rr[1]); }
;   l_reg = l_reg * alpha + ps;
; #pragma unroll
;   for (int g = 0; g < 4; ++g) {
;     int w = __builtin_amdgcn_cvt_pk_fp8_f32(p0[4 * g], p0[4 * g + 1], 0, false); p8[g] = __builtin_amdgcn_cvt_pk_fp8_f32(p0[4 * g + 2], p0[4 * g + 3], w, true);
;     int u = __builtin_amdgcn_cvt_pk_fp8_f32(p1[4 * g], p1[4 * g + 1], 0, false); p8[4 + g] = __builtin_amdgcn_cvt_pk_fp8_f32(p1[4 * g + 2], p1[4 * g + 3], u, true); }
; }
; __device__ __forceinline__ void pv8(f32x16* o, const char* Vt, const v8i32 p8, int r32, int hi) {
;   const int sw = (r32 >> 2) & 3, a0 = r32 * 64 + (((hi * 2) ^ sw) << 4), a1 = r32 * 64 + (((hi * 2 + 1) ^ sw) << 4);
; #pragma unroll
;   for (int d0 = 0; d0 < 4; ++d0) {
;     const v8i32 vf = cat8(*reinterpret_cast<const v4i32*>(Vt + d0 * 2048 + a0), *reinterpret_cast<const v4i32*>(Vt + d0 * 2048 + a1));
;     o[d0] = __builtin_amdgcn_mfma_scale_f32_32x32x64_f8f6f4(p8, vf, o[d0], 0, 0, 0, 127, 0, 127); }
; }
; __device__ __forceinline__ void attn_unit7(const unsigned char* __restrict__ Q8, int ldq, const unsigned char* __restrict__ Kn8, int ldk, const unsigned char* __restrict__ Kr8, ...
;     ...
;   for (int j = 1; j + 1 < NT; j += 2) {
;     SLOAD();
;     qkt9(pB0, pB1, Kn_lds + 8192, Kr_lds + 4096, qf, 7.0f - m_reg, r32, hi);
;     finishSM9(pA0, pA1, alA, l_reg, p8);
;     pv8(o, Vt_lds, p8, r32, hi); partialSM9(pB0, pB1, m_reg, alB, thr_raw);
;     __syncthreads(); SWRITE(0);
;     RESC(alB); __syncthreads();
;     if (j + 2 < NT) SLOAD();
;     qkt9(pA0, pA1, Kn_lds, Kr_lds, qf, 7.0f - m_reg, r32, hi);
;     finishSM9(pB0, pB1, alB, l_reg, p8);
;     pv8(o, Vt_lds + 8192, p8, r32, hi); partialSM9(pA0, pA1, m_reg, alA, thr_raw);
;     __syncthreads(); if (j + 2 < NT) SWRITE(1);
;     RESC(alA); __syncthreads();
	v_mfma_scale_f32_32x32x64_f8f6f4 v[114:129], v[82:89], v[138:145], v[114:129], v194, v193 op_sel_hi:[0,0,0]
	v_exp_f32_e32 v0, v66
	v_exp_f32_e32 v177, v67
	v_exp_f32_e32 v179, v68
	v_exp_f32_e32 v254, v69
	v_add_f32_e32 v219, v0, v219
	v_add_f32_e32 v219, v177, v219
	v_cvt_pk_fp8_f32 v250, v0, v177
	v_add_f32_e32 v219, v179, v219
	v_add_f32_e32 v219, v254, v219
	v_cvt_pk_fp8_f32 v250, v179, v254 op_sel:[0,0,1]
	s_waitcnt lgkmcnt(2)
	v_mfma_scale_f32_32x32x64_f8f6f4 v[98:113], v[222:229], v[138:145], v[98:113], v194, v193 op_sel_hi:[0,0,0]
	ds_read_b128 v[222:225], v170 offset:38912
	ds_read_b128 v[226:229], v171 offset:38912
	v_exp_f32_e32 v0, v70
	v_exp_f32_e32 v177, v71
	v_exp_f32_e32 v179, v72
	v_exp_f32_e32 v254, v73
	v_add_f32_e32 v219, v0, v219
	v_add_f32_e32 v219, v177, v219
	v_cvt_pk_fp8_f32 v251, v0, v177
	v_add_f32_e32 v219, v179, v219
	v_add_f32_e32 v219, v254, v219
	v_cvt_pk_fp8_f32 v251, v179, v254 op_sel:[0,0,1]
	v_exp_f32_e32 v0, v74
	v_exp_f32_e32 v177, v75
	v_exp_f32_e32 v179, v76
	v_exp_f32_e32 v254, v77
	v_add_f32_e32 v219, v0, v219
	v_add_f32_e32 v219, v177, v219
	v_cvt_pk_fp8_f32 v252, v0, v177
	v_add_f32_e32 v219, v179, v219
	v_add_f32_e32 v219, v254, v219
	v_cvt_pk_fp8_f32 v252, v179, v254 op_sel:[0,0,1]
	s_waitcnt lgkmcnt(2)
	v_mfma_scale_f32_32x32x64_f8f6f4 v[114:129], v[90:97], v[130:137], v[114:129], v194, v193 op_sel_hi:[0,0,0]
	v_exp_f32_e32 v0, v78
	v_exp_f32_e32 v177, v79
	v_exp_f32_e32 v179, v80
	v_exp_f32_e32 v254, v81
	v_add_f32_e32 v219, v0, v219
	v_add_f32_e32 v219, v177, v219
	v_cvt_pk_fp8_f32 v253, v0, v177
	v_add_f32_e32 v219, v179, v219
	v_add_f32_e32 v219, v254, v219
	v_cvt_pk_fp8_f32 v253, v179, v254 op_sel:[0,0,1]
	ds_read_b128 v[90:93], v170 offset:0
	ds_read_b128 v[94:97], v171 offset:0
	ds_read_b128 v[82:85], v170 offset:2048
	ds_read_b128 v[86:89], v171 offset:2048
	ds_read_b128 v[74:77], v170 offset:4096
	ds_read_b128 v[78:81], v171 offset:4096
	ds_read_b128 v[66:69], v170 offset:6144
	ds_read_b128 v[70:73], v171 offset:6144
	s_waitcnt lgkmcnt(8)
	v_mfma_scale_f32_32x32x64_f8f6f4 v[98:113], v[222:229], v[130:137], v[98:113], v194, v193 op_sel_hi:[0,0,0]
	v_mov_b32_e32 v0, v219
	s_nop 1
	v_permlane32_swap_b32_e32 v219, v0
	v_add_f32_e32 v219, v219, v0
	v_fma_f32 v209, v209, v218, v219
	v_max_f32_e32 v177, v114, v115
	v_max3_f32 v177, v177, v116, v117
	v_max3_f32 v177, v177, v118, v119
	v_max3_f32 v177, v177, v120, v121
	v_max3_f32 v177, v177, v122, v123
	v_max3_f32 v177, v177, v124, v125
	v_max3_f32 v177, v177, v126, v127
	v_max3_f32 v177, v177, v128, v129
	s_waitcnt lgkmcnt(6)
	v_mfma_scale_f32_32x32x64_f8f6f4 v[50:65], v[246:253], v[90:97], v[50:65], v194, v194 op_sel_hi:[0,0,0]
	s_waitcnt lgkmcnt(4)
	v_mfma_scale_f32_32x32x64_f8f6f4 v[34:49], v[246:253], v[82:89], v[34:49], v194, v194 op_sel_hi:[0,0,0]
	s_waitcnt lgkmcnt(2)
	v_mfma_scale_f32_32x32x64_f8f6f4 v[18:33], v[246:253], v[74:81], v[18:33], v194, v194 op_sel_hi:[0,0,0]
	s_waitcnt lgkmcnt(0)
	v_mfma_scale_f32_32x32x64_f8f6f4 v[2:17], v[246:253], v[66:73], v[2:17], v194, v194 op_sel_hi:[0,0,0]
	s_waitcnt vmcnt(0)
	ds_write_b128 v210, v[158:161]
	ds_write_b128 v211, v[162:165] offset:16384
	ds_write_b128 v212, v[154:157] offset:32768
	v_max_f32_e32 v0, v98, v99
	v_max3_f32 v0, v0, v100, v101
	v_max3_f32 v0, v0, v102, v103
	v_max3_f32 v0, v0, v104, v105
	v_max3_f32 v0, v0, v106, v107
	v_max3_f32 v0, v0, v108, v109
	v_max3_f32 v0, v0, v110, v111
	v_max3_f32 v0, v0, v112, v113
	v_max_f32_e32 v177, v177, v0
	v_mov_b32_e32 v0, v177
	v_mov_b32_e32 v221, 1.0
	s_nop 0
	v_permlane32_swap_b32_e32 v177, v0
	v_max_f32_e32 v177, v177, v0
	v_cmp_ge_f32_e32 vcc, s90, v177
	s_cmp_eq_u64 vcc, exec
	s_cbranch_scc0 .Lmla_h2_newmax
.Lmla_h2_cont:
	s_waitcnt lgkmcnt(0)
	s_barrier
	global_load_dwordx4 v[158:161], v176, s[18:19]
	global_load_dwordx4 v[162:165], v178, s[16:17]
	global_load_dwordx4 v[154:157], v[180:181], off
	ds_read_b128 v[82:85], v215 offset:16384
	ds_read_b128 v[86:89], v216 offset:16384
	ds_read_b128 v[222:225], v215 offset:20480
	ds_read_b128 v[226:229], v216 offset:20480
	v_add_u32_e32 v176, 0x2000, v176
	v_add_u32_e32 v178, 0x20000, v178
	s_mov_b64 s[20:21], 0x1000
	v_lshl_add_u64 v[180:181], v[180:181], 0, s[20:21]
	v_exp_f32_e32 v0, v114
	v_exp_f32_e32 v177, v115
	v_exp_f32_e32 v179, v116
	v_exp_f32_e32 v254, v117
	v_add_f32_e32 v219, v0, v177
	v_cvt_pk_fp8_f32 v246, v0, v177
	v_add_f32_e32 v219, v179, v219
	v_add_f32_e32 v219, v254, v219
	v_cvt_pk_fp8_f32 v246, v179, v254 op_sel:[0,0,1]
	s_waitcnt lgkmcnt(2)
	v_mfma_scale_f32_32x32x64_f8f6f4 v[82:97], v[82:89], v[146:153], v[230:245], v194, v193 op_sel_hi:[0,0,0]
	v_exp_f32_e32 v0, v118
	v_exp_f32_e32 v177, v119
	v_exp_f32_e32 v179, v120
	v_exp_f32_e32 v254, v121
	v_add_f32_e32 v219, v0, v219
	v_add_f32_e32 v219, v177, v219
	v_cvt_pk_fp8_f32 v247, v0, v177
	v_add_f32_e32 v219, v179, v219
	v_add_f32_e32 v219, v254, v219
	v_cvt_pk_fp8_f32 v247, v179, v254 op_sel:[0,0,1]
	ds_read_b128 v[114:117], v213 offset:16384
	ds_read_b128 v[118:121], v214 offset:16384
	s_waitcnt lgkmcnt(2)
	v_mfma_scale_f32_32x32x64_f8f6f4 v[66:81], v[222:229], v[146:153], v[230:245], v194, v193 op_sel_hi:[0,0,0]
	ds_read_b128 v[222:225], v213 offset:20480
	ds_read_b128 v[226:229], v214 offset:20480
	v_exp_f32_e32 v0, v122
	v_exp_f32_e32 v177, v123
	v_exp_f32_e32 v179, v124
	v_exp_f32_e32 v254, v125
	v_add_f32_e32 v219, v0, v219
	v_add_f32_e32 v219, v177, v219
	v_cvt_pk_fp8_f32 v248, v0, v177
	v_add_f32_e32 v219, v179, v219
	v_add_f32_e32 v219, v254, v219
	v_cvt_pk_fp8_f32 v248, v179, v254 op_sel:[0,0,1]
	v_exp_f32_e32 v0, v126
	v_exp_f32_e32 v177, v127
	v_exp_f32_e32 v179, v128
	v_exp_f32_e32 v254, v129
	v_add_f32_e32 v219, v0, v219
	v_add_f32_e32 v219, v177, v219
	v_cvt_pk_fp8_f32 v249, v0, v177
	v_add_f32_e32 v219, v179, v219
	v_add_f32_e32 v219, v254, v219
	v_cvt_pk_fp8_f32 v249, v179, v254 op_sel:[0,0,1]
	ds_read_b128 v[122:125], v185 offset:32768
	ds_read_b128 v[126:129], v186 offset:32768
	s_waitcnt lgkmcnt(4)
; #define SLOAD() do { vs0 = *(const bf16x8*)(Vh + voff); vs1 = *(const bf16x8*)(Vh + voff + 32u * (unsigned)ldv); \
;     ks0 = *(const bf16x8*)(Kh + koff); ks1 = *(const bf16x8*)(Kh + koff + 32u * (unsigned)ldk); \
;     if constexpr (NR > 0) { kr = *(const bf16x8*)(Krh + kroff); kroff += 64u * 64u; } voff += 64u * (unsigned)ldv; koff += 64u * (unsigned)ldk; } while (0)
; #define SWRITE(b) do { *(bf16x8*)(V_lds + (b) * SHM_V + vst0) = vs0; *(bf16x8*)(V_lds + (b) * SHM_V + vst1) = vs1; const int kc = sc * 2;  \
;     *(bf16x8*)(K_lds + (b) * SHM_K + KSWZ(sr, kc)) = ks0; *(bf16x8*)(K_lds + (b) * SHM_K + KSWZ(32 + sr, kc)) = ks1; \
;     if constexpr (NR > 0) *(bf16x8*)(Kr_lds + (b) * SHM_KR + krst) = kr; } while (0)
; #define SWRITE(b) do { *(bf16x8*)(V_lds + (b) * SHM_V + vst0) = vs0; *(bf16x8*)(V_lds + (b) * SHM_V + vst0 + 8192) = vs1;  \
;     *(bf16x8*)(K_lds + (b) * SHM_K + kst0) = ks0; *(bf16x8*)(K_lds + (b) * SHM_K + kst0 + 8192) = ks1; \
;     if constexpr (NR > 0) *(bf16x8*)(Kr_lds + (b) * SHM_KR + krst) = kr; } while (0)
; __device__ __forceinline__ void pv8(f32x16* o, const char* Vt, const v8i32 p8, int r32, int hi) {
;   const int sw = (r32 >> 2) & 3, a0 = r32 * 64 + (((hi * 2) ^ sw) << 4), a1 = r32 * 64 + (((hi * 2 + 1) ^ sw) << 4);
; #pragma unroll
;   for (int d0 = 0; d0 < 4; ++d0) {
;     const v8i32 vf = cat8(*reinterpret_cast<const v4i32*>(Vt + d0 * 2048 + a0), *reinterpret_cast<const v4i32*>(Vt + d0 * 2048 + a1));
;     o[d0] = __builtin_amdgcn_mfma_scale_f32_32x32x64_f8f6f4(p8, vf, o[d0], 0, 0, 0, 127, 0, 127); }
; }
; __device__ __forceinline__ void attn_unit7(const unsigned char* __restrict__ Q8, int ldq, const unsigned char* __restrict__ Kn8, int ldk, const unsigned char* __restrict__ Kr8, ...
;     ...
;   for (int j = 1; j + 1 < NT; j += 2) {
;     SLOAD();
;     qkt9(pB0, pB1, Kn_lds + 8192, Kr_lds + 4096, qf, 7.0f - m_reg, r32, hi);
;     finishSM9(pA0, pA1, alA, l_reg, p8);
;     pv8(o, Vt_lds, p8, r32, hi); partialSM9(pB0, pB1, m_reg, alB, thr_raw);
;     __syncthreads(); SWRITE(0);
;     RESC(alB); __syncthreads();
;     if (j + 2 < NT) SLOAD();
;     qkt9(pA0, pA1, Kn_lds, Kr_lds, qf, 7.0f - m_reg, r32, hi);
;     finishSM9(pB0, pB1, alB, l_reg, p8);
;     pv8(o, Vt_lds + 8192, p8, r32, hi); partialSM9(pA0, pA1, m_reg, alA, thr_raw);
;     __syncthreads(); if (j + 2 < NT) SWRITE(1);
;     RESC(alA); __syncthreads();
	v_mfma_scale_f32_32x32x64_f8f6f4 v[82:97], v[114:121], v[138:145], v[82:97], v194, v193 op_sel_hi:[0,0,0]
	v_exp_f32_e32 v0, v98
	v_exp_f32_e32 v177, v99
	v_exp_f32_e32 v179, v100
	v_exp_f32_e32 v254, v101
	v_add_f32_e32 v219, v0, v219
	v_add_f32_e32 v219, v177, v219
	v_cvt_pk_fp8_f32 v250, v0, v177
	v_add_f32_e32 v219, v179, v219
	v_add_f32_e32 v219, v254, v219
	v_cvt_pk_fp8_f32 v250, v179, v254 op_sel:[0,0,1]
	s_waitcnt lgkmcnt(2)
	v_mfma_scale_f32_32x32x64_f8f6f4 v[66:81], v[222:229], v[138:145], v[66:81], v194, v193 op_sel_hi:[0,0,0]
	ds_read_b128 v[222:225], v185 offset:34816
	ds_read_b128 v[226:229], v186 offset:34816
	v_exp_f32_e32 v0, v102
	v_exp_f32_e32 v177, v103
	v_exp_f32_e32 v179, v104
	v_exp_f32_e32 v254, v105
	v_add_f32_e32 v219, v0, v219
	v_add_f32_e32 v219, v177, v219
	v_cvt_pk_fp8_f32 v251, v0, v177
	v_add_f32_e32 v219, v179, v219
	v_add_f32_e32 v219, v254, v219
	v_cvt_pk_fp8_f32 v251, v179, v254 op_sel:[0,0,1]
	v_exp_f32_e32 v0, v106
	v_exp_f32_e32 v177, v107
	v_exp_f32_e32 v179, v108
	v_exp_f32_e32 v254, v109
	v_add_f32_e32 v219, v0, v219
	v_add_f32_e32 v219, v177, v219
	v_cvt_pk_fp8_f32 v252, v0, v177
	v_add_f32_e32 v219, v179, v219
	v_add_f32_e32 v219, v254, v219
	v_cvt_pk_fp8_f32 v252, v179, v254 op_sel:[0,0,1]
	s_waitcnt lgkmcnt(2)
	v_mfma_scale_f32_32x32x64_f8f6f4 v[82:97], v[122:129], v[130:137], v[82:97], v194, v193 op_sel_hi:[0,0,0]
	v_exp_f32_e32 v0, v110
	v_exp_f32_e32 v177, v111
	v_exp_f32_e32 v179, v112
	v_exp_f32_e32 v254, v113
	v_add_f32_e32 v219, v0, v219
	v_add_f32_e32 v219, v177, v219
	v_cvt_pk_fp8_f32 v253, v0, v177
	v_add_f32_e32 v219, v179, v219
	v_add_f32_e32 v219, v254, v219
	v_cvt_pk_fp8_f32 v253, v179, v254 op_sel:[0,0,1]
	ds_read_b128 v[122:125], v170 offset:8192
	ds_read_b128 v[126:129], v171 offset:8192
	ds_read_b128 v[114:117], v170 offset:10240
	ds_read_b128 v[118:121], v171 offset:10240
	ds_read_b128 v[106:109], v170 offset:12288
	ds_read_b128 v[110:113], v171 offset:12288
	ds_read_b128 v[98:101], v170 offset:14336
	ds_read_b128 v[102:105], v171 offset:14336
	s_waitcnt lgkmcnt(8)
	v_mfma_scale_f32_32x32x64_f8f6f4 v[66:81], v[222:229], v[130:137], v[66:81], v194, v193 op_sel_hi:[0,0,0]
	v_mov_b32_e32 v0, v219
	s_nop 1
	v_permlane32_swap_b32_e32 v219, v0
	v_add_f32_e32 v219, v219, v0
	v_fma_f32 v209, v209, v221, v219
	v_max_f32_e32 v177, v82, v83
	v_max3_f32 v177, v177, v84, v85
	v_max3_f32 v177, v177, v86, v87
	v_max3_f32 v177, v177, v88, v89
	v_max3_f32 v177, v177, v90, v91
	v_max3_f32 v177, v177, v92, v93
	v_max3_f32 v177, v177, v94, v95
	v_max3_f32 v177, v177, v96, v97
	s_waitcnt lgkmcnt(6)
	v_mfma_scale_f32_32x32x64_f8f6f4 v[50:65], v[246:253], v[122:129], v[50:65], v194, v194 op_sel_hi:[0,0,0]
	s_waitcnt lgkmcnt(4)
	v_mfma_scale_f32_32x32x64_f8f6f4 v[34:49], v[246:253], v[114:121], v[34:49], v194, v194 op_sel_hi:[0,0,0]
	s_waitcnt lgkmcnt(2)
	v_mfma_scale_f32_32x32x64_f8f6f4 v[18:33], v[246:253], v[106:113], v[18:33], v194, v194 op_sel_hi:[0,0,0]
	s_waitcnt lgkmcnt(0)
	v_mfma_scale_f32_32x32x64_f8f6f4 v[2:17], v[246:253], v[98:105], v[2:17], v194, v194 op_sel_hi:[0,0,0]
	s_waitcnt vmcnt(0)
	ds_write_b128 v210, v[158:161] offset:8192
	ds_write_b128 v211, v[162:165] offset:24576
	ds_write_b128 v212, v[154:157] offset:36864
	v_max_f32_e32 v0, v66, v67
	v_max3_f32 v0, v0, v68, v69
	v_max3_f32 v0, v0, v70, v71
	v_max3_f32 v0, v0, v72, v73
	v_max3_f32 v0, v0, v74, v75
	v_max3_f32 v0, v0, v76, v77
	v_max3_f32 v0, v0, v78, v79
	v_max3_f32 v0, v0, v80, v81
	v_max_f32_e32 v177, v177, v0
	v_mov_b32_e32 v0, v177
	v_mov_b32_e32 v218, 1.0
	s_nop 0
	v_permlane32_swap_b32_e32 v177, v0
	v_max_f32_e32 v177, v177, v0
	v_cmp_ge_f32_e32 vcc, s90, v177
	s_cmp_eq_u64 vcc, exec
	s_cbranch_scc0 .Lmla_h3_newmax
; __device__ __forceinline__ void finishSM9(f32x16& p0, f32x16& p1, float alpha, float& l_reg, v8i32& p8) {
; #pragma unroll
;   for (int r = 0; r < 16; ++r) { p0[r] = __builtin_amdgcn_exp2f(p0[r]); p1[r] = __builtin_amdgcn_exp2f(p1[r]); }
;   float ps = 0;
; #pragma unroll
;   for (int r = 0; r < 16; ++r) ps += p0[r];
; #pragma unroll
;   for (int r = 0; r < 16; ++r) ps += p1[r];
;   { auto rr = __builtin_amdgcn_permlane32_swap(__float_as_uint(ps), __float_as_uint(ps), false, false);
;     ps = __uint_as_float(rr[0]) + __uint_as_float(rr[1]); }
;   l_reg = l_reg * alpha + ps;
; #pragma unroll
;   for (int g = 0; g < 4; ++g) {
;     int w = __builtin_amdgcn_cvt_pk_fp8_f32(p0[4 * g], p0[4 * g + 1], 0, false); p8[g] = __builtin_amdgcn_cvt_pk_fp8_f32(p0[4 * g + 2], p0[4 * g + 3], w, true);
;     int u = __builtin_amdgcn_cvt_pk_fp8_f32(p1[4 * g], p1[4 * g + 1], 0, false); p8[4 + g] = __builtin_amdgcn_cvt_pk_fp8_f32(p1[4 * g + 2], p1[4 * g + 3], u, true); }
; }
; __device__ __forceinline__ void pv8(f32x16* o, const char* Vt, const v8i32 p8, int r32, int hi) {
;   const int sw = (r32 >> 2) & 3, a0 = r32 * 64 + (((hi * 2) ^ sw) << 4), a1 = r32 * 64 + (((hi * 2 + 1) ^ sw) << 4);
; #pragma unroll
;   for (int d0 = 0; d0 < 4; ++d0) {
;     const v8i32 vf = cat8(*reinterpret_cast<const v4i32*>(Vt + d0 * 2048 + a0), *reinterpret_cast<const v4i32*>(Vt + d0 * 2048 + a1));
; __device__ __forceinline__ void attn_unit7(const unsigned char* __restrict__ Q8, int ldq, const unsigned char* __restrict__ Kn8, int ldk, const unsigned char* __restrict__ Kr8, ...
;     ...
;   for (int j = 1; j + 1 < NT; j += 2) {
;     SLOAD();
;     qkt9(pB0, pB1, Kn_lds + 8192, Kr_lds + 4096, qf, 7.0f - m_reg, r32, hi);
;     finishSM9(pA0, pA1, alA, l_reg, p8);
;     pv8(o, Vt_lds, p8, r32, hi); partialSM9(pB0, pB1, m_reg, alB, thr_raw);
;     __syncthreads(); SWRITE(0);
;     RESC(alB); __syncthreads();
;     if (j + 2 < NT) SLOAD();
;     qkt9(pA0, pA1, Kn_lds, Kr_lds, qf, 7.0f - m_reg, r32, hi);
;     finishSM9(pB0, pB1, alB, l_reg, p8);
;     pv8(o, Vt_lds + 8192, p8, r32, hi); partialSM9(pA0, pA1, m_reg, alA, thr_raw);
;     __syncthreads(); if (j + 2 < NT) SWRITE(1);
;     RESC(alA); __syncthreads();
;   }
;   qkt9(pB0, pB1, Kn_lds + 8192, Kr_lds + 4096, qf, 7.0f - m_reg, r32, hi);
;   finishSM9(pA0, pA1, alA, l_reg, p8);
;   pv8(o, Vt_lds, p8, r32, hi); partialSM9(pB0, pB1, m_reg, alB, thr_raw);
.Lmla_h3_cont:
	s_waitcnt lgkmcnt(0)
	s_barrier
	s_add_i32 s30, s30, 1
	s_cmpk_lt_u32 s30, 63
	s_cbranch_scc1 .LBB0_1321
	global_load_dwordx4 v[158:161], v176, s[18:19]
	global_load_dwordx4 v[162:165], v178, s[16:17]
	global_load_dwordx4 v[154:157], v[180:181], off
	ds_read_b128 v[114:117], v215 offset:24576
	ds_read_b128 v[118:121], v216 offset:24576
	ds_read_b128 v[222:225], v215 offset:28672
	ds_read_b128 v[226:229], v216 offset:28672
	v_add_u32_e32 v176, 0x2000, v176
	v_add_u32_e32 v178, 0x20000, v178
	s_mov_b64 s[20:21], 0x1000
	v_lshl_add_u64 v[180:181], v[180:181], 0, s[20:21]
	v_exp_f32_e32 v0, v82
	v_exp_f32_e32 v177, v83
	v_exp_f32_e32 v179, v84
	v_exp_f32_e32 v254, v85
	v_add_f32_e32 v219, v0, v177
	v_cvt_pk_fp8_f32 v246, v0, v177
	v_add_f32_e32 v219, v179, v219
	v_add_f32_e32 v219, v254, v219
	v_cvt_pk_fp8_f32 v246, v179, v254 op_sel:[0,0,1]
	s_waitcnt lgkmcnt(2)
	v_mfma_scale_f32_32x32x64_f8f6f4 v[114:129], v[114:121], v[146:153], v[230:245], v194, v193 op_sel_hi:[0,0,0]
	v_exp_f32_e32 v0, v86
	v_exp_f32_e32 v177, v87
	v_exp_f32_e32 v179, v88
	v_exp_f32_e32 v254, v89
	v_add_f32_e32 v219, v0, v219
	v_add_f32_e32 v219, v177, v219
	v_cvt_pk_fp8_f32 v247, v0, v177
	v_add_f32_e32 v219, v179, v219
	v_add_f32_e32 v219, v254, v219
	v_cvt_pk_fp8_f32 v247, v179, v254 op_sel:[0,0,1]
	ds_read_b128 v[82:85], v213 offset:24576
	ds_read_b128 v[86:89], v214 offset:24576
	s_waitcnt lgkmcnt(2)
	v_mfma_scale_f32_32x32x64_f8f6f4 v[98:113], v[222:229], v[146:153], v[230:245], v194, v193 op_sel_hi:[0,0,0]
	ds_read_b128 v[222:225], v213 offset:28672
	ds_read_b128 v[226:229], v214 offset:28672
	v_exp_f32_e32 v0, v90
	v_exp_f32_e32 v177, v91
	v_exp_f32_e32 v179, v92
	v_exp_f32_e32 v254, v93
	v_add_f32_e32 v219, v0, v219
	v_add_f32_e32 v219, v177, v219
	v_cvt_pk_fp8_f32 v248, v0, v177
	v_add_f32_e32 v219, v179, v219
	v_add_f32_e32 v219, v254, v219
	v_cvt_pk_fp8_f32 v248, v179, v254 op_sel:[0,0,1]
	v_exp_f32_e32 v0, v94
	v_exp_f32_e32 v177, v95
	v_exp_f32_e32 v179, v96
	v_exp_f32_e32 v254, v97
	v_add_f32_e32 v219, v0, v219
	v_add_f32_e32 v219, v177, v219
	v_cvt_pk_fp8_f32 v249, v0, v177
	v_add_f32_e32 v219, v179, v219
	v_add_f32_e32 v219, v254, v219
	v_cvt_pk_fp8_f32 v249, v179, v254 op_sel:[0,0,1]
	ds_read_b128 v[90:93], v185 offset:36864
	ds_read_b128 v[94:97], v186 offset:36864
	s_waitcnt lgkmcnt(4)
	v_mfma_scale_f32_32x32x64_f8f6f4 v[114:129], v[82:89], v[138:145], v[114:129], v194, v193 op_sel_hi:[0,0,0]
	v_exp_f32_e32 v0, v66
	v_exp_f32_e32 v177, v67
	v_exp_f32_e32 v179, v68
	v_exp_f32_e32 v254, v69
	v_add_f32_e32 v219, v0, v219
	v_add_f32_e32 v219, v177, v219
	v_cvt_pk_fp8_f32 v250, v0, v177
	v_add_f32_e32 v219, v179, v219
	v_add_f32_e32 v219, v254, v219
	v_cvt_pk_fp8_f32 v250, v179, v254 op_sel:[0,0,1]
	s_waitcnt lgkmcnt(2)
	v_mfma_scale_f32_32x32x64_f8f6f4 v[98:113], v[222:229], v[138:145], v[98:113], v194, v193 op_sel_hi:[0,0,0]
	ds_read_b128 v[222:225], v185 offset:38912
	ds_read_b128 v[226:229], v186 offset:38912
	v_exp_f32_e32 v0, v70
	v_exp_f32_e32 v177, v71
	v_exp_f32_e32 v179, v72
	v_exp_f32_e32 v254, v73
	v_add_f32_e32 v219, v0, v219
	v_add_f32_e32 v219, v177, v219
	v_cvt_pk_fp8_f32 v251, v0, v177
	v_add_f32_e32 v219, v179, v219
	v_add_f32_e32 v219, v254, v219
	v_cvt_pk_fp8_f32 v251, v179, v254 op_sel:[0,0,1]
	v_exp_f32_e32 v0, v74
	v_exp_f32_e32 v177, v75
	v_exp_f32_e32 v179, v76
	v_exp_f32_e32 v254, v77
	v_add_f32_e32 v219, v0, v219
	v_add_f32_e32 v219, v177, v219
	v_cvt_pk_fp8_f32 v252, v0, v177
	v_add_f32_e32 v219, v179, v219
	v_add_f32_e32 v219, v254, v219
	v_cvt_pk_fp8_f32 v252, v179, v254 op_sel:[0,0,1]
	s_waitcnt lgkmcnt(2)
	v_mfma_scale_f32_32x32x64_f8f6f4 v[114:129], v[90:97], v[130:137], v[114:129], v194, v193 op_sel_hi:[0,0,0]
	v_exp_f32_e32 v0, v78
	v_exp_f32_e32 v177, v79
	v_exp_f32_e32 v179, v80
	v_exp_f32_e32 v254, v81
	v_add_f32_e32 v219, v0, v219
	v_add_f32_e32 v219, v177, v219
	v_cvt_pk_fp8_f32 v253, v0, v177
	v_add_f32_e32 v219, v179, v219
	v_add_f32_e32 v219, v254, v219
	v_cvt_pk_fp8_f32 v253, v179, v254 op_sel:[0,0,1]
	ds_read_b128 v[90:93], v185 offset:0
	ds_read_b128 v[94:97], v186 offset:0
	ds_read_b128 v[82:85], v185 offset:2048
	ds_read_b128 v[86:89], v186 offset:2048
	ds_read_b128 v[74:77], v185 offset:4096
	ds_read_b128 v[78:81], v186 offset:4096
	ds_read_b128 v[66:69], v185 offset:6144
	ds_read_b128 v[70:73], v186 offset:6144
	s_waitcnt lgkmcnt(8)
	v_mfma_scale_f32_32x32x64_f8f6f4 v[98:113], v[222:229], v[130:137], v[98:113], v194, v193 op_sel_hi:[0,0,0]
	v_mov_b32_e32 v0, v219
	s_nop 1
	v_permlane32_swap_b32_e32 v219, v0
	v_add_f32_e32 v219, v219, v0
	v_fma_f32 v209, v209, v218, v219
	v_max_f32_e32 v177, v114, v115
	v_max3_f32 v177, v177, v116, v117
	v_max3_f32 v177, v177, v118, v119
	v_max3_f32 v177, v177, v120, v121
	v_max3_f32 v177, v177, v122, v123
	v_max3_f32 v177, v177, v124, v125
	v_max3_f32 v177, v177, v126, v127
	v_max3_f32 v177, v177, v128, v129
	s_waitcnt lgkmcnt(6)
	v_mfma_scale_f32_32x32x64_f8f6f4 v[50:65], v[246:253], v[90:97], v[50:65], v194, v194 op_sel_hi:[0,0,0]
	s_waitcnt lgkmcnt(4)
	v_mfma_scale_f32_32x32x64_f8f6f4 v[34:49], v[246:253], v[82:89], v[34:49], v194, v194 op_sel_hi:[0,0,0]
	s_waitcnt lgkmcnt(2)
	v_mfma_scale_f32_32x32x64_f8f6f4 v[18:33], v[246:253], v[74:81], v[18:33], v194, v194 op_sel_hi:[0,0,0]
	s_waitcnt lgkmcnt(0)
	v_mfma_scale_f32_32x32x64_f8f6f4 v[2:17], v[246:253], v[66:73], v[2:17], v194, v194 op_sel_hi:[0,0,0]
	s_waitcnt vmcnt(0)
	ds_write_b128 v172, v[158:161]
	ds_write_b128 v173, v[162:165] offset:16384
	ds_write_b128 v220, v[154:157] offset:32768
	v_max_f32_e32 v0, v98, v99
	v_max3_f32 v0, v0, v100, v101
	v_max3_f32 v0, v0, v102, v103
	v_max3_f32 v0, v0, v104, v105
	v_max3_f32 v0, v0, v106, v107
	v_max3_f32 v0, v0, v108, v109
	v_max3_f32 v0, v0, v110, v111
	v_max3_f32 v0, v0, v112, v113
	v_max_f32_e32 v177, v177, v0
	v_mov_b32_e32 v0, v177
	v_mov_b32_e32 v221, 1.0
	s_nop 0
	v_permlane32_swap_b32_e32 v177, v0
	v_max_f32_e32 v177, v177, v0
	v_cmp_ge_f32_e32 vcc, s90, v177
	s_cmp_eq_u64 vcc, exec
	s_cbranch_scc0 .Lmla_p0_newmax

; __device__ __forceinline__ void finishSM9(f32x16& p0, f32x16& p1, float alpha, float& l_reg, v8i32& p8) {
; #pragma unroll
;   for (int r = 0; r < 16; ++r) { p0[r] = __builtin_amdgcn_exp2f(p0[r]); p1[r] = __builtin_amdgcn_exp2f(p1[r]); }
;   float ps = 0;
; #pragma unroll
;   for (int r = 0; r < 16; ++r) ps += p0[r];
; #pragma unroll
;   for (int r = 0; r < 16; ++r) ps += p1[r];
;   { auto rr = __builtin_amdgcn_permlane32_swap(__float_as_uint(ps), __float_as_uint(ps), false, false);
;     ps = __uint_as_float(rr[0]) + __uint_as_float(rr[1]); }
;   l_reg = l_reg * alpha + ps;
; #pragma unroll
;   for (int g = 0; g < 4; ++g) {
;     int w = __builtin_amdgcn_cvt_pk_fp8_f32(p0[4 * g], p0[4 * g + 1], 0, false); p8[g] = __builtin_amdgcn_cvt_pk_fp8_f32(p0[4 * g + 2], p0[4 * g + 3], w, true);
;     int u = __builtin_amdgcn_cvt_pk_fp8_f32(p1[4 * g], p1[4 * g + 1], 0, false); p8[4 + g] = __builtin_amdgcn_cvt_pk_fp8_f32(p1[4 * g + 2], p1[4 * g + 3], u, true); }
; }
; __device__ __forceinline__ void pv8(f32x16* o, const char* Vt, const v8i32 p8, int r32, int hi) {
;   const int sw = (r32 >> 2) & 3, a0 = r32 * 64 + (((hi * 2) ^ sw) << 4), a1 = r32 * 64 + (((hi * 2 + 1) ^ sw) << 4);
; #pragma unroll
;   for (int d0 = 0; d0 < 4; ++d0) {
;     const v8i32 vf = cat8(*reinterpret_cast<const v4i32*>(Vt + d0 * 2048 + a0), *reinterpret_cast<const v4i32*>(Vt + d0 * 2048 + a1));
;     o[d0] = __builtin_amdgcn_mfma_scale_f32_32x32x64_f8f6f4(p8, vf, o[d0], 0, 0, 0, 127, 0, 127); }
; }
; __device__ __forceinline__ void attn_unit7(const unsigned char* __restrict__ Q8, int ldq, const unsigned char* __restrict__ Kn8, int ldk, const unsigned char* __restrict__ Kr8, ...
;     ...
;   for (int j = 1; j + 1 < NT; j += 2) {
;     SLOAD();
;     qkt9(pB0, pB1, Kn_lds + 8192, Kr_lds + 4096, qf, 7.0f - m_reg, r32, hi);
;     finishSM9(pA0, pA1, alA, l_reg, p8);
;     pv8(o, Vt_lds, p8, r32, hi); partialSM9(pB0, pB1, m_reg, alB, thr_raw);
;     __syncthreads(); SWRITE(0);
;     RESC(alB); __syncthreads();
;     if (j + 2 < NT) SLOAD();
;     qkt9(pA0, pA1, Kn_lds, Kr_lds, qf, 7.0f - m_reg, r32, hi);
;     finishSM9(pB0, pB1, alB, l_reg, p8);
;     pv8(o, Vt_lds + 8192, p8, r32, hi); partialSM9(pA0, pA1, m_reg, alA, thr_raw);
;     __syncthreads(); if (j + 2 < NT) SWRITE(1);
;     RESC(alA); __syncthreads();
.Lmla_stag_loop:
	ds_read_b128 v[114:117], v215 offset:24576
	ds_read_b128 v[118:121], v216 offset:24576
	ds_read_b128 v[222:225], v215 offset:28672
	ds_read_b128 v[226:229], v216 offset:28672
	v_exp_f32_e32 v0, v82
	v_exp_f32_e32 v177, v83
	v_exp_f32_e32 v179, v84
	v_exp_f32_e32 v254, v85
	v_add_f32_e32 v219, v0, v177
	v_cvt_pk_fp8_f32 v246, v0, v177
	v_add_f32_e32 v219, v179, v219
	v_add_f32_e32 v219, v254, v219
	v_cvt_pk_fp8_f32 v246, v179, v254 op_sel:[0,0,1]
	s_waitcnt lgkmcnt(2)
	v_mfma_scale_f32_32x32x64_f8f6f4 v[114:129], v[114:121], v[146:153], v[230:245], v194, v193 op_sel_hi:[0,0,0]
	v_exp_f32_e32 v0, v86
	v_exp_f32_e32 v177, v87
	v_exp_f32_e32 v179, v88
	v_exp_f32_e32 v254, v89
	v_add_f32_e32 v219, v0, v219
	v_add_f32_e32 v219, v177, v219
	v_cvt_pk_fp8_f32 v247, v0, v177
	v_add_f32_e32 v219, v179, v219
	v_add_f32_e32 v219, v254, v219
	v_cvt_pk_fp8_f32 v247, v179, v254 op_sel:[0,0,1]
	ds_read_b128 v[82:85], v213 offset:24576
	ds_read_b128 v[86:89], v214 offset:24576
	s_waitcnt lgkmcnt(2)
	v_mfma_scale_f32_32x32x64_f8f6f4 v[98:113], v[222:229], v[146:153], v[230:245], v194, v193 op_sel_hi:[0,0,0]
	ds_read_b128 v[222:225], v213 offset:28672
	ds_read_b128 v[226:229], v214 offset:28672
	v_exp_f32_e32 v0, v90
	v_exp_f32_e32 v177, v91
	v_exp_f32_e32 v179, v92
	v_exp_f32_e32 v254, v93
	v_add_f32_e32 v219, v0, v219
	v_add_f32_e32 v219, v177, v219
	v_cvt_pk_fp8_f32 v248, v0, v177
	v_add_f32_e32 v219, v179, v219
	v_add_f32_e32 v219, v254, v219
	v_cvt_pk_fp8_f32 v248, v179, v254 op_sel:[0,0,1]
	v_exp_f32_e32 v0, v94
	v_exp_f32_e32 v177, v95
	v_exp_f32_e32 v179, v96
	v_exp_f32_e32 v254, v97
	v_add_f32_e32 v219, v0, v219
	v_add_f32_e32 v219, v177, v219
	v_cvt_pk_fp8_f32 v249, v0, v177
	v_add_f32_e32 v219, v179, v219
	v_add_f32_e32 v219, v254, v219
	v_cvt_pk_fp8_f32 v249, v179, v254 op_sel:[0,0,1]
	ds_read_b128 v[90:93], v185 offset:36864
	ds_read_b128 v[94:97], v186 offset:36864
	s_waitcnt lgkmcnt(4)
	v_mfma_scale_f32_32x32x64_f8f6f4 v[114:129], v[82:89], v[138:145], v[114:129], v194, v193 op_sel_hi:[0,0,0]
	s_waitcnt vmcnt(0)
	ds_write_b128 v172, v[158:161]
	ds_write_b128 v173, v[162:165] offset:16384
	s_waitcnt lgkmcnt(0)
	s_barrier
	global_load_dwordx4 v[158:161], v176, s[18:19]
	global_load_dwordx4 v[162:165], v178, s[16:17]
	v_add_u32_e32 v176, 0x2000, v176
	v_add_u32_e32 v178, 0x20000, v178
	v_exp_f32_e32 v0, v66
	v_exp_f32_e32 v177, v67
	v_exp_f32_e32 v179, v68
	v_exp_f32_e32 v254, v69
	v_add_f32_e32 v219, v0, v219
	v_add_f32_e32 v219, v177, v219
	v_cvt_pk_fp8_f32 v250, v0, v177
	v_add_f32_e32 v219, v179, v219
	v_add_f32_e32 v219, v254, v219
	v_cvt_pk_fp8_f32 v250, v179, v254 op_sel:[0,0,1]
	s_waitcnt lgkmcnt(2)
	v_mfma_scale_f32_32x32x64_f8f6f4 v[98:113], v[222:229], v[138:145], v[98:113], v194, v193 op_sel_hi:[0,0,0]
	ds_read_b128 v[222:225], v185 offset:38912
	ds_read_b128 v[226:229], v186 offset:38912
	v_exp_f32_e32 v0, v70
	v_exp_f32_e32 v177, v71
	v_exp_f32_e32 v179, v72
	v_exp_f32_e32 v254, v73
	v_add_f32_e32 v219, v0, v219
	v_add_f32_e32 v219, v177, v219
	v_cvt_pk_fp8_f32 v251, v0, v177
	v_add_f32_e32 v219, v179, v219
	v_add_f32_e32 v219, v254, v219
	v_cvt_pk_fp8_f32 v251, v179, v254 op_sel:[0,0,1]
	v_exp_f32_e32 v0, v74
	v_exp_f32_e32 v177, v75
	v_exp_f32_e32 v179, v76
	v_exp_f32_e32 v254, v77
	v_add_f32_e32 v219, v0, v219
	v_add_f32_e32 v219, v177, v219
	v_cvt_pk_fp8_f32 v252, v0, v177
	v_add_f32_e32 v219, v179, v219
	v_add_f32_e32 v219, v254, v219
	v_cvt_pk_fp8_f32 v252, v179, v254 op_sel:[0,0,1]
	s_waitcnt lgkmcnt(2)
	v_mfma_scale_f32_32x32x64_f8f6f4 v[114:129], v[90:97], v[130:137], v[114:129], v194, v193 op_sel_hi:[0,0,0]
	v_exp_f32_e32 v0, v78
	v_exp_f32_e32 v177, v79
	v_exp_f32_e32 v179, v80
	v_exp_f32_e32 v254, v81
	v_add_f32_e32 v219, v0, v219
	v_add_f32_e32 v219, v177, v219
	v_cvt_pk_fp8_f32 v253, v0, v177
	v_add_f32_e32 v219, v179, v219
	v_add_f32_e32 v219, v254, v219
	v_cvt_pk_fp8_f32 v253, v179, v254 op_sel:[0,0,1]
	ds_read_b128 v[90:93], v185 offset:0
	ds_read_b128 v[94:97], v186 offset:0
	ds_read_b128 v[82:85], v185 offset:2048
	ds_read_b128 v[86:89], v186 offset:2048
	ds_read_b128 v[74:77], v185 offset:4096
	ds_read_b128 v[78:81], v186 offset:4096
	ds_read_b128 v[66:69], v185 offset:6144
	ds_read_b128 v[70:73], v186 offset:6144
	s_waitcnt lgkmcnt(8)
	v_mfma_scale_f32_32x32x64_f8f6f4 v[98:113], v[222:229], v[130:137], v[98:113], v194, v193 op_sel_hi:[0,0,0]
	v_mov_b32_e32 v0, v219
	s_nop 1
	v_permlane32_swap_b32_e32 v219, v0
	v_add_f32_e32 v219, v219, v0
	v_fma_f32 v209, v209, v218, v219
	v_max_f32_e32 v177, v114, v115
	v_max3_f32 v177, v177, v116, v117
	v_max3_f32 v177, v177, v118, v119
	v_max3_f32 v177, v177, v120, v121
	v_max3_f32 v177, v177, v122, v123
	v_max3_f32 v177, v177, v124, v125
	v_max3_f32 v177, v177, v126, v127
	v_max3_f32 v177, v177, v128, v129
	s_waitcnt lgkmcnt(6)
	v_mfma_scale_f32_32x32x64_f8f6f4 v[50:65], v[246:253], v[90:97], v[50:65], v194, v194 op_sel_hi:[0,0,0]
	s_waitcnt lgkmcnt(4)
	v_mfma_scale_f32_32x32x64_f8f6f4 v[34:49], v[246:253], v[82:89], v[34:49], v194, v194 op_sel_hi:[0,0,0]
	s_waitcnt lgkmcnt(2)
	v_mfma_scale_f32_32x32x64_f8f6f4 v[18:33], v[246:253], v[74:81], v[18:33], v194, v194 op_sel_hi:[0,0,0]
	s_waitcnt lgkmcnt(0)
	v_mfma_scale_f32_32x32x64_f8f6f4 v[2:17], v[246:253], v[66:73], v[2:17], v194, v194 op_sel_hi:[0,0,0]
	v_max_f32_e32 v0, v98, v99
	v_max3_f32 v0, v0, v100, v101
	v_max3_f32 v0, v0, v102, v103
	v_max3_f32 v0, v0, v104, v105
	v_max3_f32 v0, v0, v106, v107
	v_max3_f32 v0, v0, v108, v109
	v_max3_f32 v0, v0, v110, v111
	v_max3_f32 v0, v0, v112, v113
	v_max_f32_e32 v177, v177, v0
	v_mov_b32_e32 v0, v177
	v_mov_b32_e32 v221, 1.0
	s_nop 0
	v_permlane32_swap_b32_e32 v177, v0
	v_max_f32_e32 v177, v177, v0
	v_cmp_ge_f32_e32 vcc, s90, v177
	s_cmp_eq_u64 vcc, exec
	s_cbranch_scc0 .Lmla_s0_newmax
; __device__ __forceinline__ void finishSM9(f32x16& p0, f32x16& p1, float alpha, float& l_reg, v8i32& p8) {
; #pragma unroll
;   for (int r = 0; r < 16; ++r) { p0[r] = __builtin_amdgcn_exp2f(p0[r]); p1[r] = __builtin_amdgcn_exp2f(p1[r]); }
;   float ps = 0;
; #pragma unroll
;   for (int r = 0; r < 16; ++r) ps += p0[r];
; #pragma unroll
;   for (int r = 0; r < 16; ++r) ps += p1[r];
;   { auto rr = __builtin_amdgcn_permlane32_swap(__float_as_uint(ps), __float_as_uint(ps), false, false);
;     ps = __uint_as_float(rr[0]) + __uint_as_float(rr[1]); }
;   l_reg = l_reg * alpha + ps;
; #pragma unroll
;   for (int g = 0; g < 4; ++g) {
;     int w = __builtin_amdgcn_cvt_pk_fp8_f32(p0[4 * g], p0[4 * g + 1], 0, false); p8[g] = __builtin_amdgcn_cvt_pk_fp8_f32(p0[4 * g + 2], p0[4 * g + 3], w, true);
;     int u = __builtin_amdgcn_cvt_pk_fp8_f32(p1[4 * g], p1[4 * g + 1], 0, false); p8[4 + g] = __builtin_amdgcn_cvt_pk_fp8_f32(p1[4 * g + 2], p1[4 * g + 3], u, true); }
; }
; __device__ __forceinline__ void pv8(f32x16* o, const char* Vt, const v8i32 p8, int r32, int hi) {
;   const int sw = (r32 >> 2) & 3, a0 = r32 * 64 + (((hi * 2) ^ sw) << 4), a1 = r32 * 64 + (((hi * 2 + 1) ^ sw) << 4);
; #pragma unroll
;   for (int d0 = 0; d0 < 4; ++d0) {
;     const v8i32 vf = cat8(*reinterpret_cast<const v4i32*>(Vt + d0 * 2048 + a0), *reinterpret_cast<const v4i32*>(Vt + d0 * 2048 + a1));
;     o[d0] = __builtin_amdgcn_mfma_scale_f32_32x32x64_f8f6f4(p8, vf, o[d0], 0, 0, 0, 127, 0, 127); }
; }
; __device__ __forceinline__ void attn_unit7(const unsigned char* __restrict__ Q8, int ldq, const unsigned char* __restrict__ Kn8, int ldk, const unsigned char* __restrict__ Kr8, ...
;     ...
;   for (int j = 1; j + 1 < NT; j += 2) {
;     SLOAD();
;     qkt9(pB0, pB1, Kn_lds + 8192, Kr_lds + 4096, qf, 7.0f - m_reg, r32, hi);
;     finishSM9(pA0, pA1, alA, l_reg, p8);
;     pv8(o, Vt_lds, p8, r32, hi); partialSM9(pB0, pB1, m_reg, alB, thr_raw);
;     __syncthreads(); SWRITE(0);
;     RESC(alB); __syncthreads();
;     if (j + 2 < NT) SLOAD();
;     qkt9(pA0, pA1, Kn_lds, Kr_lds, qf, 7.0f - m_reg, r32, hi);
;     finishSM9(pB0, pB1, alB, l_reg, p8);
;     pv8(o, Vt_lds + 8192, p8, r32, hi); partialSM9(pA0, pA1, m_reg, alA, thr_raw);
;     __syncthreads(); if (j + 2 < NT) SWRITE(1);
;     RESC(alA); __syncthreads();
.Lmla_s0_cont:
	ds_read_b128 v[82:85], v166 offset:16384
	ds_read_b128 v[86:89], v167 offset:16384
	ds_read_b128 v[222:225], v166 offset:20480
	ds_read_b128 v[226:229], v167 offset:20480
	v_exp_f32_e32 v0, v114
	v_exp_f32_e32 v177, v115
	v_exp_f32_e32 v179, v116
	v_exp_f32_e32 v254, v117
	v_add_f32_e32 v219, v0, v177
	v_cvt_pk_fp8_f32 v246, v0, v177
	v_add_f32_e32 v219, v179, v219
	v_add_f32_e32 v219, v254, v219
	v_cvt_pk_fp8_f32 v246, v179, v254 op_sel:[0,0,1]
	s_waitcnt lgkmcnt(2)
	v_mfma_scale_f32_32x32x64_f8f6f4 v[82:97], v[82:89], v[146:153], v[230:245], v194, v193 op_sel_hi:[0,0,0]
	v_exp_f32_e32 v0, v118
	v_exp_f32_e32 v177, v119
	v_exp_f32_e32 v179, v120
	v_exp_f32_e32 v254, v121
	v_add_f32_e32 v219, v0, v219
	v_add_f32_e32 v219, v177, v219
	v_cvt_pk_fp8_f32 v247, v0, v177
	v_add_f32_e32 v219, v179, v219
	v_add_f32_e32 v219, v254, v219
	v_cvt_pk_fp8_f32 v247, v179, v254 op_sel:[0,0,1]
	ds_read_b128 v[114:117], v168 offset:16384
	ds_read_b128 v[118:121], v169 offset:16384
	s_waitcnt lgkmcnt(2)
	v_mfma_scale_f32_32x32x64_f8f6f4 v[66:81], v[222:229], v[146:153], v[230:245], v194, v193 op_sel_hi:[0,0,0]
	ds_read_b128 v[222:225], v168 offset:20480
	ds_read_b128 v[226:229], v169 offset:20480
	v_exp_f32_e32 v0, v122
	v_exp_f32_e32 v177, v123
	v_exp_f32_e32 v179, v124
	v_exp_f32_e32 v254, v125
	v_add_f32_e32 v219, v0, v219
	v_add_f32_e32 v219, v177, v219
	v_cvt_pk_fp8_f32 v248, v0, v177
	v_add_f32_e32 v219, v179, v219
	v_add_f32_e32 v219, v254, v219
	v_cvt_pk_fp8_f32 v248, v179, v254 op_sel:[0,0,1]
	v_exp_f32_e32 v0, v126
	v_exp_f32_e32 v177, v127
	v_exp_f32_e32 v179, v128
	v_exp_f32_e32 v254, v129
	v_add_f32_e32 v219, v0, v219
	v_add_f32_e32 v219, v177, v219
	v_cvt_pk_fp8_f32 v249, v0, v177
	v_add_f32_e32 v219, v179, v219
	v_add_f32_e32 v219, v254, v219
	v_cvt_pk_fp8_f32 v249, v179, v254 op_sel:[0,0,1]
	ds_read_b128 v[122:125], v170 offset:32768
	ds_read_b128 v[126:129], v171 offset:32768
	s_waitcnt lgkmcnt(4)
	v_mfma_scale_f32_32x32x64_f8f6f4 v[82:97], v[114:121], v[138:145], v[82:97], v194, v193 op_sel_hi:[0,0,0]
	s_waitcnt vmcnt(0)
	ds_write_b128 v172, v[158:161] offset:8192
	ds_write_b128 v173, v[162:165] offset:24576
	s_waitcnt lgkmcnt(0)
	s_barrier
	global_load_dwordx4 v[158:161], v176, s[18:19]
	global_load_dwordx4 v[162:165], v178, s[16:17]
	v_add_u32_e32 v176, 0x2000, v176
	v_add_u32_e32 v178, 0x20000, v178
	v_exp_f32_e32 v0, v98
	v_exp_f32_e32 v177, v99
	v_exp_f32_e32 v179, v100
	v_exp_f32_e32 v254, v101
	v_add_f32_e32 v219, v0, v219
	v_add_f32_e32 v219, v177, v219
	v_cvt_pk_fp8_f32 v250, v0, v177
	v_add_f32_e32 v219, v179, v219
	v_add_f32_e32 v219, v254, v219
	v_cvt_pk_fp8_f32 v250, v179, v254 op_sel:[0,0,1]
	s_waitcnt lgkmcnt(2)
	v_mfma_scale_f32_32x32x64_f8f6f4 v[66:81], v[222:229], v[138:145], v[66:81], v194, v193 op_sel_hi:[0,0,0]
	ds_read_b128 v[222:225], v170 offset:34816
	ds_read_b128 v[226:229], v171 offset:34816
	v_exp_f32_e32 v0, v102
	v_exp_f32_e32 v177, v103
	v_exp_f32_e32 v179, v104
	v_exp_f32_e32 v254, v105
	v_add_f32_e32 v219, v0, v219
	v_add_f32_e32 v219, v177, v219
	v_cvt_pk_fp8_f32 v251, v0, v177
	v_add_f32_e32 v219, v179, v219
	v_add_f32_e32 v219, v254, v219
	v_cvt_pk_fp8_f32 v251, v179, v254 op_sel:[0,0,1]
	v_exp_f32_e32 v0, v106
	v_exp_f32_e32 v177, v107
	v_exp_f32_e32 v179, v108
	v_exp_f32_e32 v254, v109
	v_add_f32_e32 v219, v0, v219
	v_add_f32_e32 v219, v177, v219
	v_cvt_pk_fp8_f32 v252, v0, v177
	v_add_f32_e32 v219, v179, v219
	v_add_f32_e32 v219, v254, v219
	v_cvt_pk_fp8_f32 v252, v179, v254 op_sel:[0,0,1]
	s_waitcnt lgkmcnt(2)
	v_mfma_scale_f32_32x32x64_f8f6f4 v[82:97], v[122:129], v[130:137], v[82:97], v194, v193 op_sel_hi:[0,0,0]
	v_exp_f32_e32 v0, v110
	v_exp_f32_e32 v177, v111
	v_exp_f32_e32 v179, v112
	v_exp_f32_e32 v254, v113
	v_add_f32_e32 v219, v0, v219
	v_add_f32_e32 v219, v177, v219
	v_cvt_pk_fp8_f32 v253, v0, v177
	v_add_f32_e32 v219, v179, v219
	v_add_f32_e32 v219, v254, v219
	v_cvt_pk_fp8_f32 v253, v179, v254 op_sel:[0,0,1]
	ds_read_b128 v[122:125], v185 offset:8192
	ds_read_b128 v[126:129], v186 offset:8192
	ds_read_b128 v[114:117], v185 offset:10240
	ds_read_b128 v[118:121], v186 offset:10240
	ds_read_b128 v[106:109], v185 offset:12288
	ds_read_b128 v[110:113], v186 offset:12288
	ds_read_b128 v[98:101], v185 offset:14336
	ds_read_b128 v[102:105], v186 offset:14336
	s_waitcnt lgkmcnt(8)
	v_mfma_scale_f32_32x32x64_f8f6f4 v[66:81], v[222:229], v[130:137], v[66:81], v194, v193 op_sel_hi:[0,0,0]
	v_mov_b32_e32 v0, v219
	s_nop 1
	v_permlane32_swap_b32_e32 v219, v0
	v_add_f32_e32 v219, v219, v0
	v_fma_f32 v209, v209, v221, v219
	v_max_f32_e32 v177, v82, v83
	v_max3_f32 v177, v177, v84, v85
	v_max3_f32 v177, v177, v86, v87
	v_max3_f32 v177, v177, v88, v89
	v_max3_f32 v177, v177, v90, v91
	v_max3_f32 v177, v177, v92, v93
	v_max3_f32 v177, v177, v94, v95
	v_max3_f32 v177, v177, v96, v97
	s_waitcnt lgkmcnt(6)
	v_mfma_scale_f32_32x32x64_f8f6f4 v[50:65], v[246:253], v[122:129], v[50:65], v194, v194 op_sel_hi:[0,0,0]
	s_waitcnt lgkmcnt(4)
	v_mfma_scale_f32_32x32x64_f8f6f4 v[34:49], v[246:253], v[114:121], v[34:49], v194, v194 op_sel_hi:[0,0,0]
	s_waitcnt lgkmcnt(2)
	v_mfma_scale_f32_32x32x64_f8f6f4 v[18:33], v[246:253], v[106:113], v[18:33], v194, v194 op_sel_hi:[0,0,0]
	s_waitcnt lgkmcnt(0)
	v_mfma_scale_f32_32x32x64_f8f6f4 v[2:17], v[246:253], v[98:105], v[2:17], v194, v194 op_sel_hi:[0,0,0]
	v_max_f32_e32 v0, v66, v67
	v_max3_f32 v0, v0, v68, v69
	v_max3_f32 v0, v0, v70, v71
	v_max3_f32 v0, v0, v72, v73
	v_max3_f32 v0, v0, v74, v75
	v_max3_f32 v0, v0, v76, v77
	v_max3_f32 v0, v0, v78, v79
	v_max3_f32 v0, v0, v80, v81
	v_max_f32_e32 v177, v177, v0
	v_mov_b32_e32 v0, v177
	v_mov_b32_e32 v218, 1.0
	s_nop 0
	v_permlane32_swap_b32_e32 v177, v0
	v_max_f32_e32 v177, v177, v0
	v_cmp_ge_f32_e32 vcc, s90, v177
	s_cmp_eq_u64 vcc, exec
	s_cbranch_scc0 .Lmla_s1_newmax
; __device__ __forceinline__ void finishSM9(f32x16& p0, f32x16& p1, float alpha, float& l_reg, v8i32& p8) {
; #pragma unroll
;   for (int r = 0; r < 16; ++r) { p0[r] = __builtin_amdgcn_exp2f(p0[r]); p1[r] = __builtin_amdgcn_exp2f(p1[r]); }
;   float ps = 0;
; #pragma unroll
;   for (int r = 0; r < 16; ++r) ps += p0[r];
; #pragma unroll
;   for (int r = 0; r < 16; ++r) ps += p1[r];
;   { auto rr = __builtin_amdgcn_permlane32_swap(__float_as_uint(ps), __float_as_uint(ps), false, false);
;     ps = __uint_as_float(rr[0]) + __uint_as_float(rr[1]); }
;   l_reg = l_reg * alpha + ps;
; #pragma unroll
;   for (int g = 0; g < 4; ++g) {
;     int w = __builtin_amdgcn_cvt_pk_fp8_f32(p0[4 * g], p0[4 * g + 1], 0, false); p8[g] = __builtin_amdgcn_cvt_pk_fp8_f32(p0[4 * g + 2], p0[4 * g + 3], w, true);
;     int u = __builtin_amdgcn_cvt_pk_fp8_f32(p1[4 * g], p1[4 * g + 1], 0, false); p8[4 + g] = __builtin_amdgcn_cvt_pk_fp8_f32(p1[4 * g + 2], p1[4 * g + 3], u, true); }
; }
; __device__ __forceinline__ void pv8(f32x16* o, const char* Vt, const v8i32 p8, int r32, int hi) {
;   const int sw = (r32 >> 2) & 3, a0 = r32 * 64 + (((hi * 2) ^ sw) << 4), a1 = r32 * 64 + (((hi * 2 + 1) ^ sw) << 4);
; #pragma unroll
;   for (int d0 = 0; d0 < 4; ++d0) {
;     const v8i32 vf = cat8(*reinterpret_cast<const v4i32*>(Vt + d0 * 2048 + a0), *reinterpret_cast<const v4i32*>(Vt + d0 * 2048 + a1));
;     o[d0] = __builtin_amdgcn_mfma_scale_f32_32x32x64_f8f6f4(p8, vf, o[d0], 0, 0, 0, 127, 0, 127); }
; }
; __device__ __forceinline__ void attn_unit7(const unsigned char* __restrict__ Q8, int ldq, const unsigned char* __restrict__ Kn8, int ldk, const unsigned char* __restrict__ Kr8, ...
;     ...
;   for (int j = 1; j + 1 < NT; j += 2) {
;     SLOAD();
;     qkt9(pB0, pB1, Kn_lds + 8192, Kr_lds + 4096, qf, 7.0f - m_reg, r32, hi);
;     finishSM9(pA0, pA1, alA, l_reg, p8);
;     pv8(o, Vt_lds, p8, r32, hi); partialSM9(pB0, pB1, m_reg, alB, thr_raw);
;     __syncthreads(); SWRITE(0);
;     RESC(alB); __syncthreads();
;     if (j + 2 < NT) SLOAD();
;     qkt9(pA0, pA1, Kn_lds, Kr_lds, qf, 7.0f - m_reg, r32, hi);
;     finishSM9(pB0, pB1, alB, l_reg, p8);
;     pv8(o, Vt_lds + 8192, p8, r32, hi); partialSM9(pA0, pA1, m_reg, alA, thr_raw);
;     __syncthreads(); if (j + 2 < NT) SWRITE(1);
;     RESC(alA); __syncthreads();
.Lmla_s1_cont:
	ds_read_b128 v[114:117], v166 offset:24576
	ds_read_b128 v[118:121], v167 offset:24576
	ds_read_b128 v[222:225], v166 offset:28672
	ds_read_b128 v[226:229], v167 offset:28672
	v_exp_f32_e32 v0, v82
	v_exp_f32_e32 v177, v83
	v_exp_f32_e32 v179, v84
	v_exp_f32_e32 v254, v85
	v_add_f32_e32 v219, v0, v177
	v_cvt_pk_fp8_f32 v246, v0, v177
	v_add_f32_e32 v219, v179, v219
	v_add_f32_e32 v219, v254, v219
	v_cvt_pk_fp8_f32 v246, v179, v254 op_sel:[0,0,1]
	s_waitcnt lgkmcnt(2)
	v_mfma_scale_f32_32x32x64_f8f6f4 v[114:129], v[114:121], v[146:153], v[230:245], v194, v193 op_sel_hi:[0,0,0]
	v_exp_f32_e32 v0, v86
	v_exp_f32_e32 v177, v87
	v_exp_f32_e32 v179, v88
	v_exp_f32_e32 v254, v89
	v_add_f32_e32 v219, v0, v219
	v_add_f32_e32 v219, v177, v219
	v_cvt_pk_fp8_f32 v247, v0, v177
	v_add_f32_e32 v219, v179, v219
	v_add_f32_e32 v219, v254, v219
	v_cvt_pk_fp8_f32 v247, v179, v254 op_sel:[0,0,1]
	ds_read_b128 v[82:85], v168 offset:24576
	ds_read_b128 v[86:89], v169 offset:24576
	s_waitcnt lgkmcnt(2)
	v_mfma_scale_f32_32x32x64_f8f6f4 v[98:113], v[222:229], v[146:153], v[230:245], v194, v193 op_sel_hi:[0,0,0]
	ds_read_b128 v[222:225], v168 offset:28672
	ds_read_b128 v[226:229], v169 offset:28672
	v_exp_f32_e32 v0, v90
	v_exp_f32_e32 v177, v91
	v_exp_f32_e32 v179, v92
	v_exp_f32_e32 v254, v93
	v_add_f32_e32 v219, v0, v219
	v_add_f32_e32 v219, v177, v219
	v_cvt_pk_fp8_f32 v248, v0, v177
	v_add_f32_e32 v219, v179, v219
	v_add_f32_e32 v219, v254, v219
	v_cvt_pk_fp8_f32 v248, v179, v254 op_sel:[0,0,1]
	v_exp_f32_e32 v0, v94
	v_exp_f32_e32 v177, v95
	v_exp_f32_e32 v179, v96
	v_exp_f32_e32 v254, v97
	v_add_f32_e32 v219, v0, v219
	v_add_f32_e32 v219, v177, v219
	v_cvt_pk_fp8_f32 v249, v0, v177
	v_add_f32_e32 v219, v179, v219
	v_add_f32_e32 v219, v254, v219
	v_cvt_pk_fp8_f32 v249, v179, v254 op_sel:[0,0,1]
	ds_read_b128 v[90:93], v170 offset:36864
	ds_read_b128 v[94:97], v171 offset:36864
	s_waitcnt lgkmcnt(4)
	v_mfma_scale_f32_32x32x64_f8f6f4 v[114:129], v[82:89], v[138:145], v[114:129], v194, v193 op_sel_hi:[0,0,0]
	s_waitcnt vmcnt(0)
	ds_write_b128 v210, v[158:161]
	ds_write_b128 v211, v[162:165] offset:16384
	s_waitcnt lgkmcnt(0)
	s_barrier
	global_load_dwordx4 v[158:161], v176, s[18:19]
	global_load_dwordx4 v[162:165], v178, s[16:17]
	v_add_u32_e32 v176, 0x2000, v176
	v_add_u32_e32 v178, 0x20000, v178
	v_exp_f32_e32 v0, v66
	v_exp_f32_e32 v177, v67
	v_exp_f32_e32 v179, v68
	v_exp_f32_e32 v254, v69
	v_add_f32_e32 v219, v0, v219
	v_add_f32_e32 v219, v177, v219
	v_cvt_pk_fp8_f32 v250, v0, v177
	v_add_f32_e32 v219, v179, v219
	v_add_f32_e32 v219, v254, v219
	v_cvt_pk_fp8_f32 v250, v179, v254 op_sel:[0,0,1]
	s_waitcnt lgkmcnt(2)
	v_mfma_scale_f32_32x32x64_f8f6f4 v[98:113], v[222:229], v[138:145], v[98:113], v194, v193 op_sel_hi:[0,0,0]
	ds_read_b128 v[222:225], v170 offset:38912
	ds_read_b128 v[226:229], v171 offset:38912
	v_exp_f32_e32 v0, v70
	v_exp_f32_e32 v177, v71
	v_exp_f32_e32 v179, v72
	v_exp_f32_e32 v254, v73
	v_add_f32_e32 v219, v0, v219
	v_add_f32_e32 v219, v177, v219
	v_cvt_pk_fp8_f32 v251, v0, v177
	v_add_f32_e32 v219, v179, v219
	v_add_f32_e32 v219, v254, v219
	v_cvt_pk_fp8_f32 v251, v179, v254 op_sel:[0,0,1]
	v_exp_f32_e32 v0, v74
	v_exp_f32_e32 v177, v75
	v_exp_f32_e32 v179, v76
	v_exp_f32_e32 v254, v77
	v_add_f32_e32 v219, v0, v219
	v_add_f32_e32 v219, v177, v219
	v_cvt_pk_fp8_f32 v252, v0, v177
	v_add_f32_e32 v219, v179, v219
	v_add_f32_e32 v219, v254, v219
	v_cvt_pk_fp8_f32 v252, v179, v254 op_sel:[0,0,1]
	s_waitcnt lgkmcnt(2)
	v_mfma_scale_f32_32x32x64_f8f6f4 v[114:129], v[90:97], v[130:137], v[114:129], v194, v193 op_sel_hi:[0,0,0]
	v_exp_f32_e32 v0, v78
	v_exp_f32_e32 v177, v79
	v_exp_f32_e32 v179, v80
	v_exp_f32_e32 v254, v81
	v_add_f32_e32 v219, v0, v219
	v_add_f32_e32 v219, v177, v219
	v_cvt_pk_fp8_f32 v253, v0, v177
	v_add_f32_e32 v219, v179, v219
	v_add_f32_e32 v219, v254, v219
	v_cvt_pk_fp8_f32 v253, v179, v254 op_sel:[0,0,1]
	ds_read_b128 v[90:93], v170 offset:0
	ds_read_b128 v[94:97], v171 offset:0
	ds_read_b128 v[82:85], v170 offset:2048
	ds_read_b128 v[86:89], v171 offset:2048
	ds_read_b128 v[74:77], v170 offset:4096
	ds_read_b128 v[78:81], v171 offset:4096
	ds_read_b128 v[66:69], v170 offset:6144
	ds_read_b128 v[70:73], v171 offset:6144
	s_waitcnt lgkmcnt(8)
	v_mfma_scale_f32_32x32x64_f8f6f4 v[98:113], v[222:229], v[130:137], v[98:113], v194, v193 op_sel_hi:[0,0,0]
	v_mov_b32_e32 v0, v219
	s_nop 1
	v_permlane32_swap_b32_e32 v219, v0
	v_add_f32_e32 v219, v219, v0
	v_fma_f32 v209, v209, v218, v219
	v_max_f32_e32 v177, v114, v115
	v_max3_f32 v177, v177, v116, v117
	v_max3_f32 v177, v177, v118, v119
	v_max3_f32 v177, v177, v120, v121
	v_max3_f32 v177, v177, v122, v123
	v_max3_f32 v177, v177, v124, v125
	v_max3_f32 v177, v177, v126, v127
	v_max3_f32 v177, v177, v128, v129
	s_waitcnt lgkmcnt(6)
	v_mfma_scale_f32_32x32x64_f8f6f4 v[50:65], v[246:253], v[90:97], v[50:65], v194, v194 op_sel_hi:[0,0,0]
	s_waitcnt lgkmcnt(4)
	v_mfma_scale_f32_32x32x64_f8f6f4 v[34:49], v[246:253], v[82:89], v[34:49], v194, v194 op_sel_hi:[0,0,0]
	s_waitcnt lgkmcnt(2)
	v_mfma_scale_f32_32x32x64_f8f6f4 v[18:33], v[246:253], v[74:81], v[18:33], v194, v194 op_sel_hi:[0,0,0]
	s_waitcnt lgkmcnt(0)
	v_mfma_scale_f32_32x32x64_f8f6f4 v[2:17], v[246:253], v[66:73], v[2:17], v194, v194 op_sel_hi:[0,0,0]
	v_max_f32_e32 v0, v98, v99
	v_max3_f32 v0, v0, v100, v101
	v_max3_f32 v0, v0, v102, v103
	v_max3_f32 v0, v0, v104, v105
	v_max3_f32 v0, v0, v106, v107
	v_max3_f32 v0, v0, v108, v109
	v_max3_f32 v0, v0, v110, v111
	v_max3_f32 v0, v0, v112, v113
	v_max_f32_e32 v177, v177, v0
	v_mov_b32_e32 v0, v177
	v_mov_b32_e32 v221, 1.0
	s_nop 0
	v_permlane32_swap_b32_e32 v177, v0
	v_max_f32_e32 v177, v177, v0
	v_cmp_ge_f32_e32 vcc, s90, v177
	s_cmp_eq_u64 vcc, exec
	s_cbranch_scc0 .Lmla_s2_newmax
; __device__ __forceinline__ void finishSM9(f32x16& p0, f32x16& p1, float alpha, float& l_reg, v8i32& p8) {
; #pragma unroll
;   for (int r = 0; r < 16; ++r) { p0[r] = __builtin_amdgcn_exp2f(p0[r]); p1[r] = __builtin_amdgcn_exp2f(p1[r]); }
;   float ps = 0;
; #pragma unroll
;   for (int r = 0; r < 16; ++r) ps += p0[r];
; #pragma unroll
;   for (int r = 0; r < 16; ++r) ps += p1[r];
;   { auto rr = __builtin_amdgcn_permlane32_swap(__float_as_uint(ps), __float_as_uint(ps), false, false);
;     ps = __uint_as_float(rr[0]) + __uint_as_float(rr[1]); }
;   l_reg = l_reg * alpha + ps;
; #pragma unroll
;   for (int g = 0; g < 4; ++g) {
;     int w = __builtin_amdgcn_cvt_pk_fp8_f32(p0[4 * g], p0[4 * g + 1], 0, false); p8[g] = __builtin_amdgcn_cvt_pk_fp8_f32(p0[4 * g + 2], p0[4 * g + 3], w, true);
;     int u = __builtin_amdgcn_cvt_pk_fp8_f32(p1[4 * g], p1[4 * g + 1], 0, false); p8[4 + g] = __builtin_amdgcn_cvt_pk_fp8_f32(p1[4 * g + 2], p1[4 * g + 3], u, true); }
; }
; __device__ __forceinline__ void pv8(f32x16* o, const char* Vt, const v8i32 p8, int r32, int hi) {
;   const int sw = (r32 >> 2) & 3, a0 = r32 * 64 + (((hi * 2) ^ sw) << 4), a1 = r32 * 64 + (((hi * 2 + 1) ^ sw) << 4);
; #pragma unroll
;   for (int d0 = 0; d0 < 4; ++d0) {
;     const v8i32 vf = cat8(*reinterpret_cast<const v4i32*>(Vt + d0 * 2048 + a0), *reinterpret_cast<const v4i32*>(Vt + d0 * 2048 + a1));
;     o[d0] = __builtin_amdgcn_mfma_scale_f32_32x32x64_f8f6f4(p8, vf, o[d0], 0, 0, 0, 127, 0, 127); }
; }
; __device__ __forceinline__ void attn_unit7(const unsigned char* __restrict__ Q8, int ldq, const unsigned char* __restrict__ Kn8, int ldk, const unsigned char* __restrict__ Kr8, ...
;     ...
;   for (int j = 1; j + 1 < NT; j += 2) {
;     SLOAD();
;     qkt9(pB0, pB1, Kn_lds + 8192, Kr_lds + 4096, qf, 7.0f - m_reg, r32, hi);
;     finishSM9(pA0, pA1, alA, l_reg, p8);
;     pv8(o, Vt_lds, p8, r32, hi); partialSM9(pB0, pB1, m_reg, alB, thr_raw);
;     __syncthreads(); SWRITE(0);
;     RESC(alB); __syncthreads();
;     if (j + 2 < NT) SLOAD();
;     qkt9(pA0, pA1, Kn_lds, Kr_lds, qf, 7.0f - m_reg, r32, hi);
;     finishSM9(pB0, pB1, alB, l_reg, p8);
;     pv8(o, Vt_lds + 8192, p8, r32, hi); partialSM9(pA0, pA1, m_reg, alA, thr_raw);
;     __syncthreads(); if (j + 2 < NT) SWRITE(1);
;     RESC(alA); __syncthreads();
.Lmla_s2_cont:
	ds_read_b128 v[82:85], v215 offset:16384
	ds_read_b128 v[86:89], v216 offset:16384
	ds_read_b128 v[222:225], v215 offset:20480
	ds_read_b128 v[226:229], v216 offset:20480
	v_exp_f32_e32 v0, v114
	v_exp_f32_e32 v177, v115
	v_exp_f32_e32 v179, v116
	v_exp_f32_e32 v254, v117
	v_add_f32_e32 v219, v0, v177
	v_cvt_pk_fp8_f32 v246, v0, v177
	v_add_f32_e32 v219, v179, v219
	v_add_f32_e32 v219, v254, v219
	v_cvt_pk_fp8_f32 v246, v179, v254 op_sel:[0,0,1]
	s_waitcnt lgkmcnt(2)
	v_mfma_scale_f32_32x32x64_f8f6f4 v[82:97], v[82:89], v[146:153], v[230:245], v194, v193 op_sel_hi:[0,0,0]
	v_exp_f32_e32 v0, v118
	v_exp_f32_e32 v177, v119
	v_exp_f32_e32 v179, v120
	v_exp_f32_e32 v254, v121
	v_add_f32_e32 v219, v0, v219
	v_add_f32_e32 v219, v177, v219
	v_cvt_pk_fp8_f32 v247, v0, v177
	v_add_f32_e32 v219, v179, v219
	v_add_f32_e32 v219, v254, v219
	v_cvt_pk_fp8_f32 v247, v179, v254 op_sel:[0,0,1]
	ds_read_b128 v[114:117], v213 offset:16384
	ds_read_b128 v[118:121], v214 offset:16384
	s_waitcnt lgkmcnt(2)
	v_mfma_scale_f32_32x32x64_f8f6f4 v[66:81], v[222:229], v[146:153], v[230:245], v194, v193 op_sel_hi:[0,0,0]
	ds_read_b128 v[222:225], v213 offset:20480
	ds_read_b128 v[226:229], v214 offset:20480
	v_exp_f32_e32 v0, v122
	v_exp_f32_e32 v177, v123
	v_exp_f32_e32 v179, v124
	v_exp_f32_e32 v254, v125
	v_add_f32_e32 v219, v0, v219
	v_add_f32_e32 v219, v177, v219
	v_cvt_pk_fp8_f32 v248, v0, v177
	v_add_f32_e32 v219, v179, v219
	v_add_f32_e32 v219, v254, v219
	v_cvt_pk_fp8_f32 v248, v179, v254 op_sel:[0,0,1]
	v_exp_f32_e32 v0, v126
	v_exp_f32_e32 v177, v127
	v_exp_f32_e32 v179, v128
	v_exp_f32_e32 v254, v129
	v_add_f32_e32 v219, v0, v219
	v_add_f32_e32 v219, v177, v219
	v_cvt_pk_fp8_f32 v249, v0, v177
	v_add_f32_e32 v219, v179, v219
	v_add_f32_e32 v219, v254, v219
	v_cvt_pk_fp8_f32 v249, v179, v254 op_sel:[0,0,1]
	ds_read_b128 v[122:125], v185 offset:32768
	ds_read_b128 v[126:129], v186 offset:32768
	s_waitcnt lgkmcnt(4)
	v_mfma_scale_f32_32x32x64_f8f6f4 v[82:97], v[114:121], v[138:145], v[82:97], v194, v193 op_sel_hi:[0,0,0]
	s_waitcnt vmcnt(0)
	ds_write_b128 v210, v[158:161] offset:8192
	ds_write_b128 v211, v[162:165] offset:24576
	s_waitcnt lgkmcnt(0)
	s_barrier
	global_load_dwordx4 v[158:161], v176, s[18:19]
	global_load_dwordx4 v[162:165], v178, s[16:17]
	v_add_u32_e32 v176, 0x2000, v176
	v_add_u32_e32 v178, 0x20000, v178
	v_exp_f32_e32 v0, v98
	v_exp_f32_e32 v177, v99
	v_exp_f32_e32 v179, v100
	v_exp_f32_e32 v254, v101
	v_add_f32_e32 v219, v0, v219
	v_add_f32_e32 v219, v177, v219
	v_cvt_pk_fp8_f32 v250, v0, v177
	v_add_f32_e32 v219, v179, v219
	v_add_f32_e32 v219, v254, v219
	v_cvt_pk_fp8_f32 v250, v179, v254 op_sel:[0,0,1]
	s_waitcnt lgkmcnt(2)
	v_mfma_scale_f32_32x32x64_f8f6f4 v[66:81], v[222:229], v[138:145], v[66:81], v194, v193 op_sel_hi:[0,0,0]
	ds_read_b128 v[222:225], v185 offset:34816
	ds_read_b128 v[226:229], v186 offset:34816
	v_exp_f32_e32 v0, v102
	v_exp_f32_e32 v177, v103
	v_exp_f32_e32 v179, v104
	v_exp_f32_e32 v254, v105
	v_add_f32_e32 v219, v0, v219
	v_add_f32_e32 v219, v177, v219
	v_cvt_pk_fp8_f32 v251, v0, v177
	v_add_f32_e32 v219, v179, v219
	v_add_f32_e32 v219, v254, v219
	v_cvt_pk_fp8_f32 v251, v179, v254 op_sel:[0,0,1]
	v_exp_f32_e32 v0, v106
	v_exp_f32_e32 v177, v107
	v_exp_f32_e32 v179, v108
	v_exp_f32_e32 v254, v109
	v_add_f32_e32 v219, v0, v219
	v_add_f32_e32 v219, v177, v219
	v_cvt_pk_fp8_f32 v252, v0, v177
	v_add_f32_e32 v219, v179, v219
	v_add_f32_e32 v219, v254, v219
	v_cvt_pk_fp8_f32 v252, v179, v254 op_sel:[0,0,1]
	s_waitcnt lgkmcnt(2)
	v_mfma_scale_f32_32x32x64_f8f6f4 v[82:97], v[122:129], v[130:137], v[82:97], v194, v193 op_sel_hi:[0,0,0]
	v_exp_f32_e32 v0, v110
	v_exp_f32_e32 v177, v111
	v_exp_f32_e32 v179, v112
	v_exp_f32_e32 v254, v113
	v_add_f32_e32 v219, v0, v219
	v_add_f32_e32 v219, v177, v219
	v_cvt_pk_fp8_f32 v253, v0, v177
	v_add_f32_e32 v219, v179, v219
	v_add_f32_e32 v219, v254, v219
	v_cvt_pk_fp8_f32 v253, v179, v254 op_sel:[0,0,1]
	ds_read_b128 v[122:125], v170 offset:8192
	ds_read_b128 v[126:129], v171 offset:8192
	ds_read_b128 v[114:117], v170 offset:10240
	ds_read_b128 v[118:121], v171 offset:10240
	ds_read_b128 v[106:109], v170 offset:12288
	ds_read_b128 v[110:113], v171 offset:12288
	ds_read_b128 v[98:101], v170 offset:14336
	ds_read_b128 v[102:105], v171 offset:14336
	s_waitcnt lgkmcnt(8)
	v_mfma_scale_f32_32x32x64_f8f6f4 v[66:81], v[222:229], v[130:137], v[66:81], v194, v193 op_sel_hi:[0,0,0]
	v_mov_b32_e32 v0, v219
	s_nop 1
	v_permlane32_swap_b32_e32 v219, v0
	v_add_f32_e32 v219, v219, v0
	v_fma_f32 v209, v209, v221, v219
	v_max_f32_e32 v177, v82, v83
	v_max3_f32 v177, v177, v84, v85
	v_max3_f32 v177, v177, v86, v87
	v_max3_f32 v177, v177, v88, v89
	v_max3_f32 v177, v177, v90, v91
	v_max3_f32 v177, v177, v92, v93
	v_max3_f32 v177, v177, v94, v95
	v_max3_f32 v177, v177, v96, v97
	s_waitcnt lgkmcnt(6)
	v_mfma_scale_f32_32x32x64_f8f6f4 v[50:65], v[246:253], v[122:129], v[50:65], v194, v194 op_sel_hi:[0,0,0]
	s_waitcnt lgkmcnt(4)
	v_mfma_scale_f32_32x32x64_f8f6f4 v[34:49], v[246:253], v[114:121], v[34:49], v194, v194 op_sel_hi:[0,0,0]
	s_waitcnt lgkmcnt(2)
	v_mfma_scale_f32_32x32x64_f8f6f4 v[18:33], v[246:253], v[106:113], v[18:33], v194, v194 op_sel_hi:[0,0,0]
	s_waitcnt lgkmcnt(0)
	v_mfma_scale_f32_32x32x64_f8f6f4 v[2:17], v[246:253], v[98:105], v[2:17], v194, v194 op_sel_hi:[0,0,0]
	v_max_f32_e32 v0, v66, v67
	v_max3_f32 v0, v0, v68, v69
	v_max3_f32 v0, v0, v70, v71
	v_max3_f32 v0, v0, v72, v73
	v_max3_f32 v0, v0, v74, v75
	v_max3_f32 v0, v0, v76, v77
	v_max3_f32 v0, v0, v78, v79
	v_max3_f32 v0, v0, v80, v81
	v_max_f32_e32 v177, v177, v0
	v_mov_b32_e32 v0, v177
	v_mov_b32_e32 v218, 1.0
	s_nop 0
	v_permlane32_swap_b32_e32 v177, v0
	v_max_f32_e32 v177, v177, v0
	v_cmp_ge_f32_e32 vcc, s90, v177
	s_cmp_eq_u64 vcc, exec
	s_cbranch_scc0 .Lmla_s3_newmax
; __device__ __forceinline__ void finishSM9(f32x16& p0, f32x16& p1, float alpha, float& l_reg, v8i32& p8) {
; #pragma unroll
;   for (int r = 0; r < 16; ++r) { p0[r] = __builtin_amdgcn_exp2f(p0[r]); p1[r] = __builtin_amdgcn_exp2f(p1[r]); }
;   float ps = 0;
; #pragma unroll
;   for (int r = 0; r < 16; ++r) ps += p0[r];
; #pragma unroll
;   for (int r = 0; r < 16; ++r) ps += p1[r];
;   { auto rr = __builtin_amdgcn_permlane32_swap(__float_as_uint(ps), __float_as_uint(ps), false, false);
;     ps = __uint_as_float(rr[0]) + __uint_as_float(rr[1]); }
;   l_reg = l_reg * alpha + ps;
; #pragma unroll
;   for (int g = 0; g < 4; ++g) {
;     int w = __builtin_amdgcn_cvt_pk_fp8_f32(p0[4 * g], p0[4 * g + 1], 0, false); p8[g] = __builtin_amdgcn_cvt_pk_fp8_f32(p0[4 * g + 2], p0[4 * g + 3], w, true);
;     int u = __builtin_amdgcn_cvt_pk_fp8_f32(p1[4 * g], p1[4 * g + 1], 0, false); p8[4 + g] = __builtin_amdgcn_cvt_pk_fp8_f32(p1[4 * g + 2], p1[4 * g + 3], u, true); }
; }
; __device__ __forceinline__ void pv8(f32x16* o, const char* Vt, const v8i32 p8, int r32, int hi) {
;   const int sw = (r32 >> 2) & 3, a0 = r32 * 64 + (((hi * 2) ^ sw) << 4), a1 = r32 * 64 + (((hi * 2 + 1) ^ sw) << 4);
; #pragma unroll
;   for (int d0 = 0; d0 < 4; ++d0) {
;     const v8i32 vf = cat8(*reinterpret_cast<const v4i32*>(Vt + d0 * 2048 + a0), *reinterpret_cast<const v4i32*>(Vt + d0 * 2048 + a1));
; __device__ __forceinline__ void attn_unit7(const unsigned char* __restrict__ Q8, int ldq, const unsigned char* __restrict__ Kn8, int ldk, const unsigned char* __restrict__ Kr8, ...
;     ...
;   for (int j = 1; j + 1 < NT; j += 2) {
;     SLOAD();
;     qkt9(pB0, pB1, Kn_lds + 8192, Kr_lds + 4096, qf, 7.0f - m_reg, r32, hi);
;     finishSM9(pA0, pA1, alA, l_reg, p8);
;     pv8(o, Vt_lds, p8, r32, hi); partialSM9(pB0, pB1, m_reg, alB, thr_raw);
;     __syncthreads(); SWRITE(0);
;     RESC(alB); __syncthreads();
;     if (j + 2 < NT) SLOAD();
;     qkt9(pA0, pA1, Kn_lds, Kr_lds, qf, 7.0f - m_reg, r32, hi);
;     finishSM9(pB0, pB1, alB, l_reg, p8);
;     pv8(o, Vt_lds + 8192, p8, r32, hi); partialSM9(pA0, pA1, m_reg, alA, thr_raw);
;     __syncthreads(); if (j + 2 < NT) SWRITE(1);
;     RESC(alA); __syncthreads();
;   }
;   qkt9(pB0, pB1, Kn_lds + 8192, Kr_lds + 4096, qf, 7.0f - m_reg, r32, hi);
;   finishSM9(pA0, pA1, alA, l_reg, p8);
;   pv8(o, Vt_lds, p8, r32, hi); partialSM9(pB0, pB1, m_reg, alB, thr_raw);
.Lmla_s3_cont:
	s_add_i32 s30, s30, 1
	s_cmpk_lt_u32 s30, 63
	s_cbranch_scc1 .Lmla_stag_loop
	ds_read_b128 v[114:117], v215 offset:24576
	ds_read_b128 v[118:121], v216 offset:24576
	ds_read_b128 v[222:225], v215 offset:28672
	ds_read_b128 v[226:229], v216 offset:28672
	v_exp_f32_e32 v0, v82
	v_exp_f32_e32 v177, v83
	v_exp_f32_e32 v179, v84
	v_exp_f32_e32 v254, v85
	v_add_f32_e32 v219, v0, v177
	v_cvt_pk_fp8_f32 v246, v0, v177
	v_add_f32_e32 v219, v179, v219
	v_add_f32_e32 v219, v254, v219
	v_cvt_pk_fp8_f32 v246, v179, v254 op_sel:[0,0,1]
	s_waitcnt lgkmcnt(2)
	v_mfma_scale_f32_32x32x64_f8f6f4 v[114:129], v[114:121], v[146:153], v[230:245], v194, v193 op_sel_hi:[0,0,0]
	v_exp_f32_e32 v0, v86
	v_exp_f32_e32 v177, v87
	v_exp_f32_e32 v179, v88
	v_exp_f32_e32 v254, v89
	v_add_f32_e32 v219, v0, v219
	v_add_f32_e32 v219, v177, v219
	v_cvt_pk_fp8_f32 v247, v0, v177
	v_add_f32_e32 v219, v179, v219
	v_add_f32_e32 v219, v254, v219
	v_cvt_pk_fp8_f32 v247, v179, v254 op_sel:[0,0,1]
	ds_read_b128 v[82:85], v213 offset:24576
	ds_read_b128 v[86:89], v214 offset:24576
	s_waitcnt lgkmcnt(2)
	v_mfma_scale_f32_32x32x64_f8f6f4 v[98:113], v[222:229], v[146:153], v[230:245], v194, v193 op_sel_hi:[0,0,0]
	ds_read_b128 v[222:225], v213 offset:28672
	ds_read_b128 v[226:229], v214 offset:28672
	v_exp_f32_e32 v0, v90
	v_exp_f32_e32 v177, v91
	v_exp_f32_e32 v179, v92
	v_exp_f32_e32 v254, v93
	v_add_f32_e32 v219, v0, v219
	v_add_f32_e32 v219, v177, v219
	v_cvt_pk_fp8_f32 v248, v0, v177
	v_add_f32_e32 v219, v179, v219
	v_add_f32_e32 v219, v254, v219
	v_cvt_pk_fp8_f32 v248, v179, v254 op_sel:[0,0,1]
	v_exp_f32_e32 v0, v94
	v_exp_f32_e32 v177, v95
	v_exp_f32_e32 v179, v96
	v_exp_f32_e32 v254, v97
	v_add_f32_e32 v219, v0, v219
	v_add_f32_e32 v219, v177, v219
	v_cvt_pk_fp8_f32 v249, v0, v177
	v_add_f32_e32 v219, v179, v219
	v_add_f32_e32 v219, v254, v219
	v_cvt_pk_fp8_f32 v249, v179, v254 op_sel:[0,0,1]
	ds_read_b128 v[90:93], v185 offset:36864
	ds_read_b128 v[94:97], v186 offset:36864
	s_waitcnt lgkmcnt(4)
	v_mfma_scale_f32_32x32x64_f8f6f4 v[114:129], v[82:89], v[138:145], v[114:129], v194, v193 op_sel_hi:[0,0,0]
	s_waitcnt vmcnt(0)
	ds_write_b128 v172, v[158:161]
	ds_write_b128 v173, v[162:165] offset:16384
	s_waitcnt lgkmcnt(0)
	s_barrier
	global_load_dwordx4 v[158:161], v176, s[18:19]
	global_load_dwordx4 v[162:165], v178, s[16:17]
	v_add_u32_e32 v176, 0x2000, v176
	v_add_u32_e32 v178, 0x20000, v178
	v_exp_f32_e32 v0, v66
	v_exp_f32_e32 v177, v67
	v_exp_f32_e32 v179, v68
	v_exp_f32_e32 v254, v69
	v_add_f32_e32 v219, v0, v219
	v_add_f32_e32 v219, v177, v219
	v_cvt_pk_fp8_f32 v250, v0, v177
	v_add_f32_e32 v219, v179, v219
	v_add_f32_e32 v219, v254, v219
	v_cvt_pk_fp8_f32 v250, v179, v254 op_sel:[0,0,1]
	s_waitcnt lgkmcnt(2)
	v_mfma_scale_f32_32x32x64_f8f6f4 v[98:113], v[222:229], v[138:145], v[98:113], v194, v193 op_sel_hi:[0,0,0]
	ds_read_b128 v[222:225], v185 offset:38912
	ds_read_b128 v[226:229], v186 offset:38912
	v_exp_f32_e32 v0, v70
	v_exp_f32_e32 v177, v71
	v_exp_f32_e32 v179, v72
	v_exp_f32_e32 v254, v73
	v_add_f32_e32 v219, v0, v219
	v_add_f32_e32 v219, v177, v219
	v_cvt_pk_fp8_f32 v251, v0, v177
	v_add_f32_e32 v219, v179, v219
	v_add_f32_e32 v219, v254, v219
	v_cvt_pk_fp8_f32 v251, v179, v254 op_sel:[0,0,1]
	v_exp_f32_e32 v0, v74
	v_exp_f32_e32 v177, v75
	v_exp_f32_e32 v179, v76
	v_exp_f32_e32 v254, v77
	v_add_f32_e32 v219, v0, v219
	v_add_f32_e32 v219, v177, v219
	v_cvt_pk_fp8_f32 v252, v0, v177
	v_add_f32_e32 v219, v179, v219
	v_add_f32_e32 v219, v254, v219
	v_cvt_pk_fp8_f32 v252, v179, v254 op_sel:[0,0,1]
	s_waitcnt lgkmcnt(2)
	v_mfma_scale_f32_32x32x64_f8f6f4 v[114:129], v[90:97], v[130:137], v[114:129], v194, v193 op_sel_hi:[0,0,0]
	v_exp_f32_e32 v0, v78
	v_exp_f32_e32 v177, v79
	v_exp_f32_e32 v179, v80
	v_exp_f32_e32 v254, v81
	v_add_f32_e32 v219, v0, v219
	v_add_f32_e32 v219, v177, v219
	v_cvt_pk_fp8_f32 v253, v0, v177
	v_add_f32_e32 v219, v179, v219
	v_add_f32_e32 v219, v254, v219
	v_cvt_pk_fp8_f32 v253, v179, v254 op_sel:[0,0,1]
	ds_read_b128 v[90:93], v185 offset:0
	ds_read_b128 v[94:97], v186 offset:0
	ds_read_b128 v[82:85], v185 offset:2048
	ds_read_b128 v[86:89], v186 offset:2048
	ds_read_b128 v[74:77], v185 offset:4096
	ds_read_b128 v[78:81], v186 offset:4096
	ds_read_b128 v[66:69], v185 offset:6144
	ds_read_b128 v[70:73], v186 offset:6144
	s_waitcnt lgkmcnt(8)
	v_mfma_scale_f32_32x32x64_f8f6f4 v[98:113], v[222:229], v[130:137], v[98:113], v194, v193 op_sel_hi:[0,0,0]
	v_mov_b32_e32 v0, v219
	s_nop 1
	v_permlane32_swap_b32_e32 v219, v0
	v_add_f32_e32 v219, v219, v0
	v_fma_f32 v209, v209, v218, v219
	v_max_f32_e32 v177, v114, v115
	v_max3_f32 v177, v177, v116, v117
	v_max3_f32 v177, v177, v118, v119
	v_max3_f32 v177, v177, v120, v121
	v_max3_f32 v177, v177, v122, v123
	v_max3_f32 v177, v177, v124, v125
	v_max3_f32 v177, v177, v126, v127
	v_max3_f32 v177, v177, v128, v129
	s_waitcnt lgkmcnt(6)
	v_mfma_scale_f32_32x32x64_f8f6f4 v[50:65], v[246:253], v[90:97], v[50:65], v194, v194 op_sel_hi:[0,0,0]
	s_waitcnt lgkmcnt(4)
	v_mfma_scale_f32_32x32x64_f8f6f4 v[34:49], v[246:253], v[82:89], v[34:49], v194, v194 op_sel_hi:[0,0,0]
	s_waitcnt lgkmcnt(2)
	v_mfma_scale_f32_32x32x64_f8f6f4 v[18:33], v[246:253], v[74:81], v[18:33], v194, v194 op_sel_hi:[0,0,0]
	s_waitcnt lgkmcnt(0)
	v_mfma_scale_f32_32x32x64_f8f6f4 v[2:17], v[246:253], v[66:73], v[2:17], v194, v194 op_sel_hi:[0,0,0]
	v_max_f32_e32 v0, v98, v99
	v_max3_f32 v0, v0, v100, v101
	v_max3_f32 v0, v0, v102, v103
	v_max3_f32 v0, v0, v104, v105
	v_max3_f32 v0, v0, v106, v107
	v_max3_f32 v0, v0, v108, v109
	v_max3_f32 v0, v0, v110, v111
	v_max3_f32 v0, v0, v112, v113
	v_max_f32_e32 v177, v177, v0
	v_mov_b32_e32 v0, v177
	v_mov_b32_e32 v221, 1.0
	s_nop 0
	v_permlane32_swap_b32_e32 v177, v0
	v_max_f32_e32 v177, v177, v0
	v_cmp_ge_f32_e32 vcc, s90, v177
	s_cmp_eq_u64 vcc, exec
	s_cbranch_scc0 .Lmla_q0_newmax
; __device__ __forceinline__ void finishSM9(f32x16& p0, f32x16& p1, float alpha, float& l_reg, v8i32& p8) {
; #pragma unroll
;   for (int r = 0; r < 16; ++r) { p0[r] = __builtin_amdgcn_exp2f(p0[r]); p1[r] = __builtin_amdgcn_exp2f(p1[r]); }
;   float ps = 0;
; #pragma unroll
;   for (int r = 0; r < 16; ++r) ps += p0[r];
; #pragma unroll
;   for (int r = 0; r < 16; ++r) ps += p1[r];
;   { auto rr = __builtin_amdgcn_permlane32_swap(__float_as_uint(ps), __float_as_uint(ps), false, false);
;     ps = __uint_as_float(rr[0]) + __uint_as_float(rr[1]); }
;   l_reg = l_reg * alpha + ps;
; #pragma unroll
;   for (int g = 0; g < 4; ++g) {
;     int w = __builtin_amdgcn_cvt_pk_fp8_f32(p0[4 * g], p0[4 * g + 1], 0, false); p8[g] = __builtin_amdgcn_cvt_pk_fp8_f32(p0[4 * g + 2], p0[4 * g + 3], w, true);
;     int u = __builtin_amdgcn_cvt_pk_fp8_f32(p1[4 * g], p1[4 * g + 1], 0, false); p8[4 + g] = __builtin_amdgcn_cvt_pk_fp8_f32(p1[4 * g + 2], p1[4 * g + 3], u, true); }
; }
; __device__ __forceinline__ void pv8(f32x16* o, const char* Vt, const v8i32 p8, int r32, int hi) {
;   const int sw = (r32 >> 2) & 3, a0 = r32 * 64 + (((hi * 2) ^ sw) << 4), a1 = r32 * 64 + (((hi * 2 + 1) ^ sw) << 4);
; #pragma unroll
;   for (int d0 = 0; d0 < 4; ++d0) {
;     const v8i32 vf = cat8(*reinterpret_cast<const v4i32*>(Vt + d0 * 2048 + a0), *reinterpret_cast<const v4i32*>(Vt + d0 * 2048 + a1));
;     o[d0] = __builtin_amdgcn_mfma_scale_f32_32x32x64_f8f6f4(p8, vf, o[d0], 0, 0, 0, 127, 0, 127); }
; }
; __device__ __forceinline__ void qkt9(f32x16& p0, f32x16& p1, const char* Kn, const char* Kr, const v8i32* qf, const float init, int r32, int hi) {
; #pragma unroll
;   for (int r = 0; r < 16; ++r) { p0[r] = init; p1[r] = init; }
; #pragma unroll
;   for (int s = 0; s < 2; ++s) { const int c0 = s * 4 + hi * 2;
;     const v8i32 a0 = cat8(*reinterpret_cast<const v4i32*>(Kn + KN8SW(r32, c0)), *reinterpret_cast<const v4i32*>(Kn + KN8SW(r32, c0 + 1)));
; __device__ __forceinline__ void attn_unit7(const unsigned char* __restrict__ Q8, int ldq, const unsigned char* __restrict__ Kn8, int ldk, const unsigned char* __restrict__ Kr8, ...
;     ...
;   qkt9(pB0, pB1, Kn_lds + 8192, Kr_lds + 4096, qf, 7.0f - m_reg, r32, hi);
;   finishSM9(pA0, pA1, alA, l_reg, p8);
;   pv8(o, Vt_lds, p8, r32, hi); partialSM9(pB0, pB1, m_reg, alB, thr_raw);
.Lmla_q0_cont:
	ds_read_b128 v[82:85], v166 offset:16384
	ds_read_b128 v[86:89], v167 offset:16384
	ds_read_b128 v[222:225], v166 offset:20480
	ds_read_b128 v[226:229], v167 offset:20480
	v_exp_f32_e32 v0, v114
	v_exp_f32_e32 v177, v115
	v_exp_f32_e32 v179, v116
	v_exp_f32_e32 v254, v117
	v_add_f32_e32 v219, v0, v177
	v_cvt_pk_fp8_f32 v246, v0, v177
	v_add_f32_e32 v219, v179, v219
	v_add_f32_e32 v219, v254, v219
	v_cvt_pk_fp8_f32 v246, v179, v254 op_sel:[0,0,1]
	s_waitcnt lgkmcnt(2)
	v_mfma_scale_f32_32x32x64_f8f6f4 v[82:97], v[82:89], v[146:153], v[230:245], v194, v193 op_sel_hi:[0,0,0]
	v_exp_f32_e32 v0, v118
	v_exp_f32_e32 v177, v119
	v_exp_f32_e32 v179, v120
	v_exp_f32_e32 v254, v121
	v_add_f32_e32 v219, v0, v219
	v_add_f32_e32 v219, v177, v219
	v_cvt_pk_fp8_f32 v247, v0, v177
	v_add_f32_e32 v219, v179, v219
	v_add_f32_e32 v219, v254, v219
	v_cvt_pk_fp8_f32 v247, v179, v254 op_sel:[0,0,1]
	ds_read_b128 v[114:117], v168 offset:16384
	ds_read_b128 v[118:121], v169 offset:16384
	s_waitcnt lgkmcnt(2)
	v_mfma_scale_f32_32x32x64_f8f6f4 v[66:81], v[222:229], v[146:153], v[230:245], v194, v193 op_sel_hi:[0,0,0]
	ds_read_b128 v[222:225], v168 offset:20480
	ds_read_b128 v[226:229], v169 offset:20480
	v_exp_f32_e32 v0, v122
	v_exp_f32_e32 v177, v123
	v_exp_f32_e32 v179, v124
	v_exp_f32_e32 v254, v125
	v_add_f32_e32 v219, v0, v219
	v_add_f32_e32 v219, v177, v219
	v_cvt_pk_fp8_f32 v248, v0, v177
	v_add_f32_e32 v219, v179, v219
	v_add_f32_e32 v219, v254, v219
	v_cvt_pk_fp8_f32 v248, v179, v254 op_sel:[0,0,1]
	v_exp_f32_e32 v0, v126
	v_exp_f32_e32 v177, v127
	v_exp_f32_e32 v179, v128
	v_exp_f32_e32 v254, v129
	v_add_f32_e32 v219, v0, v219
	v_add_f32_e32 v219, v177, v219
	v_cvt_pk_fp8_f32 v249, v0, v177
	v_add_f32_e32 v219, v179, v219
	v_add_f32_e32 v219, v254, v219
	v_cvt_pk_fp8_f32 v249, v179, v254 op_sel:[0,0,1]
	ds_read_b128 v[122:125], v170 offset:32768
	ds_read_b128 v[126:129], v171 offset:32768
	s_waitcnt lgkmcnt(4)
	v_mfma_scale_f32_32x32x64_f8f6f4 v[82:97], v[114:121], v[138:145], v[82:97], v194, v193 op_sel_hi:[0,0,0]
	s_waitcnt vmcnt(0)
	ds_write_b128 v172, v[158:161] offset:8192
	ds_write_b128 v173, v[162:165] offset:24576
	s_waitcnt lgkmcnt(0)
	s_barrier
	v_exp_f32_e32 v0, v98
	v_exp_f32_e32 v177, v99
	v_exp_f32_e32 v179, v100
	v_exp_f32_e32 v254, v101
	v_add_f32_e32 v219, v0, v219
	v_add_f32_e32 v219, v177, v219
	v_cvt_pk_fp8_f32 v250, v0, v177
	v_add_f32_e32 v219, v179, v219
	v_add_f32_e32 v219, v254, v219
	v_cvt_pk_fp8_f32 v250, v179, v254 op_sel:[0,0,1]
	s_waitcnt lgkmcnt(2)
	v_mfma_scale_f32_32x32x64_f8f6f4 v[66:81], v[222:229], v[138:145], v[66:81], v194, v193 op_sel_hi:[0,0,0]
	ds_read_b128 v[222:225], v170 offset:34816
	ds_read_b128 v[226:229], v171 offset:34816
	v_exp_f32_e32 v0, v102
	v_exp_f32_e32 v177, v103
	v_exp_f32_e32 v179, v104
	v_exp_f32_e32 v254, v105
	v_add_f32_e32 v219, v0, v219
	v_add_f32_e32 v219, v177, v219
	v_cvt_pk_fp8_f32 v251, v0, v177
	v_add_f32_e32 v219, v179, v219
	v_add_f32_e32 v219, v254, v219
	v_cvt_pk_fp8_f32 v251, v179, v254 op_sel:[0,0,1]
	v_exp_f32_e32 v0, v106
	v_exp_f32_e32 v177, v107
	v_exp_f32_e32 v179, v108
	v_exp_f32_e32 v254, v109
	v_add_f32_e32 v219, v0, v219
	v_add_f32_e32 v219, v177, v219
	v_cvt_pk_fp8_f32 v252, v0, v177
	v_add_f32_e32 v219, v179, v219
	v_add_f32_e32 v219, v254, v219
	v_cvt_pk_fp8_f32 v252, v179, v254 op_sel:[0,0,1]
	s_waitcnt lgkmcnt(2)
	v_mfma_scale_f32_32x32x64_f8f6f4 v[82:97], v[122:129], v[130:137], v[82:97], v194, v193 op_sel_hi:[0,0,0]
	v_exp_f32_e32 v0, v110
	v_exp_f32_e32 v177, v111
	v_exp_f32_e32 v179, v112
	v_exp_f32_e32 v254, v113
	v_add_f32_e32 v219, v0, v219
	v_add_f32_e32 v219, v177, v219
	v_cvt_pk_fp8_f32 v253, v0, v177
	v_add_f32_e32 v219, v179, v219
	v_add_f32_e32 v219, v254, v219
	v_cvt_pk_fp8_f32 v253, v179, v254 op_sel:[0,0,1]
	ds_read_b128 v[122:125], v185 offset:8192
	ds_read_b128 v[126:129], v186 offset:8192
	ds_read_b128 v[114:117], v185 offset:10240
	ds_read_b128 v[118:121], v186 offset:10240
	ds_read_b128 v[106:109], v185 offset:12288
	ds_read_b128 v[110:113], v186 offset:12288
	ds_read_b128 v[98:101], v185 offset:14336
	ds_read_b128 v[102:105], v186 offset:14336
	s_waitcnt lgkmcnt(8)
	v_mfma_scale_f32_32x32x64_f8f6f4 v[66:81], v[222:229], v[130:137], v[66:81], v194, v193 op_sel_hi:[0,0,0]
	v_mov_b32_e32 v0, v219
	s_nop 1
	v_permlane32_swap_b32_e32 v219, v0
	v_add_f32_e32 v219, v219, v0
	v_fma_f32 v209, v209, v221, v219
	v_max_f32_e32 v177, v82, v83
	v_max3_f32 v177, v177, v84, v85
	v_max3_f32 v177, v177, v86, v87
	v_max3_f32 v177, v177, v88, v89
	v_max3_f32 v177, v177, v90, v91
	v_max3_f32 v177, v177, v92, v93
	v_max3_f32 v177, v177, v94, v95
	v_max3_f32 v177, v177, v96, v97
	s_waitcnt lgkmcnt(6)
	v_mfma_scale_f32_32x32x64_f8f6f4 v[50:65], v[246:253], v[122:129], v[50:65], v194, v194 op_sel_hi:[0,0,0]
	s_waitcnt lgkmcnt(4)
	v_mfma_scale_f32_32x32x64_f8f6f4 v[34:49], v[246:253], v[114:121], v[34:49], v194, v194 op_sel_hi:[0,0,0]
	s_waitcnt lgkmcnt(2)
	v_mfma_scale_f32_32x32x64_f8f6f4 v[18:33], v[246:253], v[106:113], v[18:33], v194, v194 op_sel_hi:[0,0,0]
	s_waitcnt lgkmcnt(0)
	v_mfma_scale_f32_32x32x64_f8f6f4 v[2:17], v[246:253], v[98:105], v[2:17], v194, v194 op_sel_hi:[0,0,0]
	v_max_f32_e32 v0, v66, v67
	v_max3_f32 v0, v0, v68, v69
	v_max3_f32 v0, v0, v70, v71
	v_max3_f32 v0, v0, v72, v73
	v_max3_f32 v0, v0, v74, v75
	v_max3_f32 v0, v0, v76, v77
	v_max3_f32 v0, v0, v78, v79
	v_max3_f32 v0, v0, v80, v81
	v_max_f32_e32 v177, v177, v0
	v_mov_b32_e32 v0, v177
	v_mov_b32_e32 v218, 1.0
	s_nop 0
	v_permlane32_swap_b32_e32 v177, v0
	v_max_f32_e32 v177, v177, v0
	v_cmp_ge_f32_e32 vcc, s90, v177
	s_cmp_eq_u64 vcc, exec
	s_cbranch_scc0 .Lmla_q1_newmax

; __device__ __forceinline__ void qkt9(f32x16& p0, f32x16& p1, const char* Kn, const char* Kr, const v8i32* qf, const float init, int r32, int hi) {
; #pragma unroll
;   for (int r = 0; r < 16; ++r) { p0[r] = init; p1[r] = init; }
; #pragma unroll
;   for (int s = 0; s < 2; ++s) { const int c0 = s * 4 + hi * 2;
;     const v8i32 a0 = cat8(*reinterpret_cast<const v4i32*>(Kn + KN8SW(r32, c0)), *reinterpret_cast<const v4i32*>(Kn + KN8SW(r32, c0 + 1)));
;     const v8i32 a1 = cat8(*reinterpret_cast<const v4i32*>(Kn + 4096 + KN8SW(r32, c0)), *reinterpret_cast<const v4i32*>(Kn + 4096 + KN8SW(r32, c0 + 1)));
;     p0 = __builtin_amdgcn_mfma_scale_f32_32x32x64_f8f6f4(a0, qf[s], p0, 0, 0, 0, 127, 0, 124);
;     p1 = __builtin_amdgcn_mfma_scale_f32_32x32x64_f8f6f4(a1, qf[s], p1, 0, 0, 0, 127, 0, 124); }
;   { const int c0 = hi * 2;
;     const v8i32 a0 = cat8(*reinterpret_cast<const v4i32*>(Kr + KR8SW(r32, c0)), *reinterpret_cast<const v4i32*>(Kr + KR8SW(r32, c0 + 1)));
;     const v8i32 a1 = cat8(*reinterpret_cast<const v4i32*>(Kr + 2048 + KR8SW(r32, c0)), *reinterpret_cast<const v4i32*>(Kr + 2048 + KR8SW(r32, c0 + 1)));
;     p0 = __builtin_amdgcn_mfma_scale_f32_32x32x64_f8f6f4(a0, qf[2], p0, 0, 0, 0, 127, 0, 124);
;     p1 = __builtin_amdgcn_mfma_scale_f32_32x32x64_f8f6f4(a1, qf[2], p1, 0, 0, 0, 127, 0, 124); }
; }
; __device__ __forceinline__ void partialSM9(f32x16& p0, f32x16& p1, float& m_run, float& alpha, const float thr2) {
;   float pmax = p0[0];
; #pragma unroll
;   for (int r = 1; r < 16; ++r) pmax = fmaxf(pmax, p0[r]);
; #pragma unroll
;   for (int r = 0; r < 16; ++r) pmax = fmaxf(pmax, p1[r]);
;   { auto rr = __builtin_amdgcn_permlane32_swap(__float_as_uint(pmax), __float_as_uint(pmax), false, false);
;     pmax = fmaxf(__uint_as_float(rr[0]), __uint_as_float(rr[1])); }
;   if (__builtin_expect(__all(pmax <= 7.0f + thr2), 1)) { alpha = 1.f; }
; __device__ __forceinline__ void attn_unit7(const unsigned char* __restrict__ Q8, int ldq, const unsigned char* __restrict__ Kn8, int ldk, const unsigned char* __restrict__ Kr8, ...
;     ...
;   qkt9(pB0, pB1, Kn_lds + 8192, Kr_lds + 4096, qf, 7.0f - m_reg, r32, hi);
;   finishSM9(pA0, pA1, alA, l_reg, p8);
;   pv8(o, Vt_lds, p8, r32, hi); partialSM9(pB0, pB1, m_reg, alB, thr_raw);
;   RESC(alB);
;   finishSM9(pB0, pB1, alB, l_reg, p8);
.LBB0_1343:
	ds_read_b128 v[114:117], v166 offset:24576
	ds_read_b128 v[118:121], v167 offset:24576
	ds_read_b128 v[154:157], v166 offset:28672
	ds_read_b128 v[158:161], v167 offset:28672
	v_sub_f32_e32 v98, 0x40e00000, v217
	v_mov_b32_e32 v99, v98
	v_mov_b32_e32 v100, v98
	v_mov_b32_e32 v101, v98
	v_mov_b32_e32 v102, v98
	v_mov_b32_e32 v103, v98
	v_mov_b32_e32 v104, v98
	v_mov_b32_e32 v105, v98
	v_mov_b32_e32 v106, v98
	v_mov_b32_e32 v107, v98
	v_mov_b32_e32 v108, v98
	v_mov_b32_e32 v109, v98
	v_mov_b32_e32 v110, v98
	v_mov_b32_e32 v111, v98
	v_mov_b32_e32 v112, v98
	v_mov_b32_e32 v113, v98
	v_exp_f32_e32 v162, v91
	v_exp_f32_e32 v163, v95
	s_waitcnt lgkmcnt(2)
	v_mfma_scale_f32_32x32x64_f8f6f4 v[114:129], v[114:121], v[146:153], v[98:113], v194, v193 op_sel_hi:[0,0,0]
	v_exp_f32_e32 v164, v81
	s_waitcnt lgkmcnt(0)
	v_mfma_scale_f32_32x32x64_f8f6f4 v[98:113], v[154:161], v[146:153], v[98:113], v194, v193 op_sel_hi:[0,0,0]
	ds_read_b128 v[146:149], v168 offset:24576
	ds_read_b128 v[150:153], v169 offset:24576
	ds_read_b128 v[154:157], v168 offset:28672
	ds_read_b128 v[158:161], v169 offset:28672
	s_waitcnt lgkmcnt(2)
	v_mfma_scale_f32_32x32x64_f8f6f4 v[114:129], v[146:153], v[138:145], v[114:129], v194, v193 op_sel_hi:[0,0,0]
	s_waitcnt lgkmcnt(0)
	v_mfma_scale_f32_32x32x64_f8f6f4 v[98:113], v[154:161], v[138:145], v[98:113], v194, v193 op_sel_hi:[0,0,0]
	ds_read_b128 v[138:141], v170 offset:36864
	ds_read_b128 v[142:145], v171 offset:36864
	ds_read_b128 v[146:149], v170 offset:38912
	ds_read_b128 v[150:153], v171 offset:38912
	v_exp_f32_e32 v160, v83
	v_exp_f32_e32 v154, v86
	v_exp_f32_e32 v161, v87
	v_exp_f32_e32 v158, v90
	v_exp_f32_e32 v159, v94
	v_exp_f32_e32 v157, v97
	v_exp_f32_e32 v155, v75
	v_exp_f32_e32 v156, v79
	s_waitcnt lgkmcnt(2)
	v_mfma_scale_f32_32x32x64_f8f6f4 v[114:129], v[138:145], v[130:137], v[114:129], v194, v193 op_sel_hi:[0,0,0]
	v_exp_f32_e32 v141, v82
	v_exp_f32_e32 v143, v66
	v_exp_f32_e32 v145, v88
	v_exp_f32_e32 v139, v93
	v_add_f32_e32 v66, 0, v141
	v_add_f32_e32 v66, v160, v66
	v_exp_f32_e32 v138, v69
	v_exp_f32_e32 v144, v70
	v_exp_f32_e32 v142, v72
	v_exp_f32_e32 v140, v77
	s_nop 9
	v_max_f32_e32 v165, v114, v114
	s_waitcnt lgkmcnt(0)
	v_mfma_scale_f32_32x32x64_f8f6f4 v[98:113], v[146:153], v[130:137], v[98:113], v194, v193 op_sel_hi:[0,0,0]
	v_exp_f32_e32 v133, v84
	v_exp_f32_e32 v137, v85
	v_exp_f32_e32 v153, v89
	v_exp_f32_e32 v135, v92
	v_add_f32_e32 v66, v133, v66
	v_add_f32_e32 v66, v137, v66
	v_add_f32_e32 v66, v154, v66
	v_add_f32_e32 v66, v161, v66
	v_add_f32_e32 v66, v145, v66
	v_add_f32_e32 v66, v153, v66
	v_add_f32_e32 v66, v158, v66
	v_add_f32_e32 v66, v162, v66
	v_exp_f32_e32 v150, v96
	v_add_f32_e32 v66, v135, v66
	v_add_f32_e32 v66, v139, v66
	v_add_f32_e32 v66, v159, v66
	v_exp_f32_e32 v151, v67
	v_add_f32_e32 v66, v163, v66
	v_exp_f32_e32 v134, v68
	v_add_f32_e32 v66, v150, v66
	v_add_f32_e32 v66, v157, v66
	v_add_f32_e32 v66, v143, v66
	v_exp_f32_e32 v152, v71
	v_add_f32_e32 v66, v151, v66
	v_add_f32_e32 v66, v134, v66
	v_exp_f32_e32 v147, v73
	v_add_f32_e32 v66, v138, v66
	v_max_f32_e32 v132, v115, v115
	v_exp_f32_e32 v148, v74
	v_add_f32_e32 v66, v144, v66
	v_max_f32_e32 v132, v165, v132
	v_add_f32_e32 v66, v152, v66
	v_max3_f32 v132, v132, v116, v117
	v_exp_f32_e32 v136, v76
	v_add_f32_e32 v66, v142, v66
	v_max3_f32 v132, v132, v118, v119
	v_add_f32_e32 v66, v147, v66
	v_max3_f32 v132, v132, v120, v121
	v_exp_f32_e32 v149, v78
	v_add_f32_e32 v66, v148, v66
	v_max3_f32 v132, v132, v122, v123
	v_add_f32_e32 v66, v155, v66
	v_max3_f32 v132, v132, v124, v125
	v_exp_f32_e32 v146, v80
	v_add_f32_e32 v66, v136, v66
	v_max3_f32 v132, v132, v126, v127
	v_add_f32_e32 v66, v140, v66
	v_max3_f32 v132, v132, v128, v129
	v_add_f32_e32 v66, v149, v66
	v_max3_f32 v132, v132, v98, v99
	v_add_f32_e32 v66, v156, v66
	v_max3_f32 v132, v132, v100, v101
	v_add_f32_e32 v66, v146, v66
	v_max3_f32 v132, v132, v102, v103
	v_add_f32_e32 v130, v164, v66
	ds_read_b128 v[90:93], v170
	ds_read_b128 v[94:97], v171
	ds_read_b128 v[82:85], v170 offset:2048
	ds_read_b128 v[86:89], v171 offset:2048
	ds_read_b128 v[74:77], v170 offset:4096
	ds_read_b128 v[78:81], v171 offset:4096
	ds_read_b128 v[66:69], v170 offset:6144
	ds_read_b128 v[70:73], v171 offset:6144
	v_max3_f32 v132, v132, v104, v105
	v_max3_f32 v132, v132, v106, v107
	v_max3_f32 v132, v132, v108, v109
	v_max3_f32 v132, v132, v110, v111
	v_max3_f32 v132, v132, v112, v113
	v_mov_b32_e32 v165, v132
	s_nop 1
	v_permlane32_swap_b32_e32 v132, v165
	v_max_f32_e32 v165, v165, v165
	v_max_f32_e32 v132, v132, v132
	v_max_f32_e32 v165, v132, v165
	v_mov_b32_e32 v131, v130
	v_cmp_ge_f32_e32 vcc, s90, v165
	s_nop 0
	v_permlane32_swap_b32_e32 v130, v131
	v_mov_b32_e32 v132, 1.0
	s_cmp_eq_u64 vcc, exec
	s_cbranch_scc0 .LBB0_1351

; __device__ __forceinline__ void finishSM9(f32x16& p0, f32x16& p1, float alpha, float& l_reg, v8i32& p8) {
; #pragma unroll
;   for (int r = 0; r < 16; ++r) { p0[r] = __builtin_amdgcn_exp2f(p0[r]); p1[r] = __builtin_amdgcn_exp2f(p1[r]); }
;   float ps = 0;
; #pragma unroll
;   for (int r = 0; r < 16; ++r) ps += p0[r];
; #pragma unroll
;   for (int r = 0; r < 16; ++r) ps += p1[r];
;   { auto rr = __builtin_amdgcn_permlane32_swap(__float_as_uint(ps), __float_as_uint(ps), false, false);
;     ps = __uint_as_float(rr[0]) + __uint_as_float(rr[1]); }
;   l_reg = l_reg * alpha + ps;
; #pragma unroll
;   for (int g = 0; g < 4; ++g) {
;     int w = __builtin_amdgcn_cvt_pk_fp8_f32(p0[4 * g], p0[4 * g + 1], 0, false); p8[g] = __builtin_amdgcn_cvt_pk_fp8_f32(p0[4 * g + 2], p0[4 * g + 3], w, true);
;     int u = __builtin_amdgcn_cvt_pk_fp8_f32(p1[4 * g], p1[4 * g + 1], 0, false); p8[4 + g] = __builtin_amdgcn_cvt_pk_fp8_f32(p1[4 * g + 2], p1[4 * g + 3], u, true); }
; }
; __device__ __forceinline__ void attn_unit7(const unsigned char* __restrict__ Q8, int ldq, const unsigned char* __restrict__ Kn8, int ldk, const unsigned char* __restrict__ Kr8, ...
;     ...
;   finishSM9(pB0, pB1, alB, l_reg, p8);
;   pv8(o, Vt_lds + 8192, p8, r32, hi);
;   if (hi == 0) li_l[r32] = l_reg; asm volatile("s_waitcnt lgkmcnt(0)" ::: "memory");
.LBB0_1348:
	v_exp_f32_e32 v139, v114
	v_exp_f32_e32 v141, v115
	v_exp_f32_e32 v114, v116
	v_exp_f32_e32 v116, v117
	v_exp_f32_e32 v140, v118
	v_add_f32_e32 v66, 0, v139
	v_exp_f32_e32 v142, v119
	v_add_f32_e32 v66, v141, v66
	v_exp_f32_e32 v119, v120
	v_add_f32_e32 v66, v114, v66
	v_exp_f32_e32 v138, v121
	v_add_f32_e32 v66, v116, v66
	v_exp_f32_e32 v120, v122
	v_add_f32_e32 v66, v140, v66
	v_exp_f32_e32 v122, v123
	v_add_f32_e32 v66, v142, v66
	v_exp_f32_e32 v133, v98
	v_exp_f32_e32 v98, v124
	v_add_f32_e32 v66, v119, v66
	v_exp_f32_e32 v115, v100
	v_exp_f32_e32 v100, v125
	v_add_f32_e32 v66, v138, v66
	v_exp_f32_e32 v121, v126
	v_add_f32_e32 v66, v120, v66
	v_exp_f32_e32 v118, v104
	v_exp_f32_e32 v104, v110
	v_exp_f32_e32 v110, v127
	v_add_f32_e32 v66, v122, v66
	v_exp_f32_e32 v135, v105
	v_exp_f32_e32 v105, v128
	v_add_f32_e32 v66, v98, v66
	v_exp_f32_e32 v117, v101
	v_exp_f32_e32 v101, v109
	v_exp_f32_e32 v109, v129
	v_add_f32_e32 v66, v100, v66
	v_add_f32_e32 v66, v121, v66
	v_exp_f32_e32 v136, v99
	v_add_f32_e32 v66, v110, v66
	v_add_f32_e32 v66, v105, v66
	v_add_f32_e32 v66, v109, v66
	v_exp_f32_e32 v134, v102
	v_add_f32_e32 v66, v133, v66
	v_exp_f32_e32 v137, v103
	v_add_f32_e32 v66, v136, v66
	v_add_f32_e32 v66, v115, v66
	v_add_f32_e32 v66, v117, v66
	v_exp_f32_e32 v103, v106
	v_add_f32_e32 v66, v134, v66
	v_exp_f32_e32 v107, v107
	v_add_f32_e32 v66, v137, v66
	v_exp_f32_e32 v99, v108
	v_add_f32_e32 v66, v118, v66
	v_add_f32_e32 v66, v135, v66
	v_add_f32_e32 v66, v103, v66
	v_exp_f32_e32 v108, v111
	v_add_f32_e32 v66, v107, v66
	v_exp_f32_e32 v102, v112
	v_add_f32_e32 v66, v99, v66
	v_add_f32_e32 v66, v101, v66
	v_add_f32_e32 v66, v104, v66
	v_add_f32_e32 v66, v108, v66
	v_add_f32_e32 v111, v102, v66
	ds_read_b128 v[90:93], v170 offset:8192
	ds_read_b128 v[82:85], v170 offset:10240
	ds_read_b128 v[94:97], v171 offset:8192
	ds_read_b128 v[86:89], v171 offset:10240
	ds_read_b128 v[74:77], v170 offset:12288
	ds_read_b128 v[66:69], v170 offset:14336
	ds_read_b128 v[78:81], v171 offset:12288
	ds_read_b128 v[70:73], v171 offset:14336
	v_exp_f32_e32 v106, v113
	s_nop 0
	v_add_f32_e32 v111, v106, v111
	v_mov_b32_e32 v112, v111
	s_nop 1
	v_permlane32_swap_b32_e32 v111, v112
	s_and_saveexec_b64 s[16:17], s[40:41]
	s_cbranch_execz .LBB0_1310
	v_add_f32_e32 v113, v130, v131
	v_fmac_f32_e32 v113, v209, v0
	v_add_f32_e32 v0, v111, v112
	v_fmac_f32_e32 v0, v113, v132
	ds_write_b32 v208, v0 offset:40960
	s_branch .LBB0_1310

; #define GEMM_PHASE(MODE, Aoff, Boff, N_, K_, F0, FO) do { pg8::Gemm g{WB(Aoff), WB(Boff), S_, (N_), (K_)}; int G_ = gridDim.x, bx_ = blockIdx.x; asm volatile("" : "+s"(G_), "+s"(bx_)); pg8::StaticOrder SO; SO.init(S_, (N_), G_, bx_); \
;     pg8::Epi<pg8::MODE> E{{ws, (F0), (FO)}}; pg8::gemm_phase<pg8::Epi<pg8::MODE>, pg8::StaticOrder, true, true>((LAS unsigned char*)lds, g, SO, E); } while (0)
;     __host__ __device__ bool next(int i, Unit& u) const {
;         const long L = (long)i * G + c; if (L >= nwg) return false;
;         int wgid = (int)L; { const int q = nwg / NXCD, r = nwg % NXCD, xcd = wgid % NXCD, off = wgid / NXCD; wgid = (xcd < r ? xcd * (q + 1) : r * (q + 1) + (xcd - r) * q) + off; }
;         const int nig = WGM * nN, gid = wgid / nig, fm = gid * WGM, gsz = (nM - fm) < WGM ? (nM - fm) : WGM;
;         u.pm = fm + ((wgid % nig) % gsz); u.pn = (wgid % nig) / gsz; return true;
; __global__ void __launch_bounds__(NWAVES * 64, 2) mega_fwd(Args args) {
;     ...
;             GEMM_PHASE(EP_YA, WS_OA, WS_WOA, DM, 512, nullptr, nullptr);
.LBB0_1352:
	v_mov_b64_e32 v[166:167], 0x9c0
	v_mov_b64_e32 v[168:169], 0x9bf
	v_mov_b64_e32 v[170:171], 0x200
	v_mov_b64_e32 v[172:173], 0x1ff
	s_mov_b32 s2, s92
	s_mov_b32 s3, s68
	v_mov_b32_e32 v0, v189
	s_cmpk_gt_i32 s2, 0x1ff
	v_readfirstlane_b32 s15, v0
	s_cbranch_scc1 .LBB0_1376
	s_ashr_i32 s5, s2, 31
	s_lshr_b32 s10, s5, 29
	s_add_i32 s14, s2, s10
	s_and_b32 s10, s14, -8
	s_sub_i32 s12, s2, s10
	s_cmp_gt_i32 s12, -1
	s_mov_b64 s[10:11], -1
	s_cbranch_scc0 .LBB0_1355
	s_lshl_b32 s13, s12, 6
	s_mov_b64 s[10:11], 0
